# nt also on concat-buffer stores (attention combine + conv) and on the read-once Q loads in the attention phase, on top of v22
# speedup vs baseline: 1.0071x; 1.0002x over previous
.LBB0_300:
	s_and_b32 s13, s9, 1
	s_cmp_lt_u32 s9, 2
	s_cselect_b32 s48, s92, s91
	s_lshl_b32 s0, s13, 7
	s_add_u32 s4, s93, s0
	s_addc_u32 s10, s94, 0
	s_waitcnt lgkmcnt(1)
	v_mov_b32_e32 v36, v0
	s_add_u32 s0, s95, s0
	s_addc_u32 s1, s96, 0
	v_readfirstlane_b32 s5, v36
	s_ashr_i32 s12, s5, 6
	s_lshl_b32 s49, s48, 8
	s_lshl_b32 s44, s12, 5
	s_add_i32 s40, s44, s49
	s_ashr_i32 s41, s40, 31
	v_and_b32_e32 v232, 63, v36
	s_lshl_b64 s[30:31], s[40:41], 12
	s_add_u32 s42, s4, s30
	v_lshlrev_b32_e32 v2, 12, v232
	s_addc_u32 s43, s10, s31
	s_waitcnt vmcnt(3)
	v_lshl_add_u64 v[4:5], s[0:1], 0, v[2:3]
	s_lshl_b32 s0, s12, 3
	s_ashr_i32 s1, s0, 31
	v_lshl_add_u64 v[224:225], s[0:1], 1, v[4:5]
	s_lshl_b32 s0, s12, 4
	v_bfe_u32 v2, v36, 2, 4
	v_and_or_b32 v2, s0, 48, v2
	s_ashr_i32 s0, s5, 3
	s_andn2_b32 s0, s0, 31
	v_lshlrev_b32_e32 v2, 12, v2
	s_ashr_i32 s1, s0, 31
	s_lshl_b32 s4, s12, 10
	v_lshl_add_u64 v[4:5], s[38:39], 0, v[2:3]
	v_lshlrev_b32_e32 v235, 3, v36
	s_cmp_lg_u32 0, -1
	v_lshl_add_u64 v[4:5], s[0:1], 1, v[4:5]
	v_and_b32_e32 v236, 24, v235
	s_cselect_b32 s0, 0, 0
	v_lshlrev_b32_e32 v2, 1, v236
	s_add_i32 s15, s4, s0
	s_mov_b32 s0, m0
	s_mov_b32 m0, s15
	s_nop 0
	global_load_lds_dwordx4 v[224:225], off
	s_mov_b32 m0, s0
	v_and_b32_e32 v233, 31, v36
	v_lshl_add_u64 v[226:227], v[4:5], 0, v[2:3]
	s_add_i32 s31, s15, 0x6000
	s_mov_b32 s0, m0
	s_mov_b32 m0, s31
	s_nop 0
	global_load_lds_dwordx4 v[226:227], off
	s_mov_b32 m0, s0
	v_bfe_u32 v218, v36, 5, 1
	v_lshl_add_u64 v[228:229], v[226:227], 0, s[18:19]
	s_add_i32 s0, s15, 0x8000
	s_mov_b32 s1, m0
	s_mov_b32 m0, s0
	s_nop 0
	global_load_lds_dwordx4 v[228:229], off
	s_mov_b32 m0, s1
	v_lshlrev_b32_e32 v2, 12, v233
	v_lshl_add_u64 v[4:5], v[224:225], 0, s[20:21]
	s_add_i32 s0, s15, 0x2000
	s_mov_b32 s1, m0
	s_mov_b32 m0, s0
	s_nop 0
	global_load_lds_dwordx4 v[4:5], off
	s_mov_b32 m0, s1
	v_lshl_or_b32 v2, v218, 4, v2
	global_load_dwordx4 v[174:177], v2, s[42:43] nt
	global_load_dwordx4 v[166:169], v2, s[42:43] offset:32 nt
	global_load_dwordx4 v[154:157], v2, s[42:43] offset:64 nt
	global_load_dwordx4 v[146:149], v2, s[42:43] offset:96 nt
	v_lshlrev_b32_e32 v2, 10, v218
	v_lshlrev_b32_e32 v4, 4, v233
	v_add3_u32 v242, 0, v2, v4
	v_lshl_add_u64 v[4:5], v[224:225], 0, s[22:23]
	s_add_i32 s0, s15, 0x4000
	s_mov_b32 s1, m0
	s_mov_b32 m0, s0
	s_nop 0
	global_load_lds_dwordx4 v[4:5], off
	s_mov_b32 m0, s1
	s_waitcnt vmcnt(3) lgkmcnt(0)
	s_barrier
	ds_read_b128 v[4:7], v242
	ds_read_b128 v[20:23], v242 offset:512
	ds_read_b128 v[38:41], v242 offset:2048
	s_cmp_lg_u32 s48, 0
	s_cselect_b64 s[0:1], -1, 0
	v_lshlrev_b32_e32 v234, 2, v218
	v_or_b32_e32 v241, s44, v233
	s_and_b64 vcc, exec, s[0:1]
	s_waitcnt vmcnt(3) lgkmcnt(2)
	v_mfma_f32_32x32x16_bf16 v[4:19], v[4:7], v[174:177], 0
	s_waitcnt vmcnt(2) lgkmcnt(0)
	v_mfma_f32_32x32x16_bf16 v[4:19], v[38:41], v[166:169], v[4:19]
	ds_read_b128 v[38:41], v242 offset:2560
	v_mfma_f32_32x32x16_bf16 v[20:35], v[20:23], v[174:177], 0
	s_waitcnt lgkmcnt(0)
	v_mfma_f32_32x32x16_bf16 v[20:35], v[38:41], v[166:169], v[20:35]
	ds_read_b128 v[38:41], v242 offset:4096
	s_waitcnt vmcnt(1) lgkmcnt(0)
	v_mfma_f32_32x32x16_bf16 v[4:19], v[38:41], v[154:157], v[4:19]
	ds_read_b128 v[38:41], v242 offset:4608
	s_waitcnt lgkmcnt(0)
	v_mfma_f32_32x32x16_bf16 v[20:35], v[38:41], v[154:157], v[20:35]
	ds_read_b128 v[38:41], v242 offset:6144
	s_waitcnt vmcnt(0) lgkmcnt(0)
	v_mfma_f32_32x32x16_bf16 v[4:19], v[38:41], v[146:149], v[4:19]
	ds_read_b128 v[38:41], v242 offset:6656
	s_waitcnt lgkmcnt(0)
	v_mfma_f32_32x32x16_bf16 v[20:35], v[38:41], v[146:149], v[20:35]
	s_nop 15
	s_nop 7
	s_cbranch_vccnz .LBB0_302
	v_lshlrev_b32_e32 v2, 2, v218
	v_or_b32_e32 v37, 32, v2
	v_cmp_le_i32_e32 vcc, v37, v241
	v_or_b32_e32 v37, 33, v2
	s_nop 6
	v_cndmask_b32_e32 v20, v230, v20, vcc
	v_cmp_lt_i32_e32 vcc, v2, v241
	s_nop 1
	v_cndmask_b32_e32 v5, v230, v5, vcc
	v_cmp_le_i32_e32 vcc, v2, v241
	s_nop 1
	v_cndmask_b32_e32 v4, v230, v4, vcc
	v_cmp_le_i32_e32 vcc, v37, v241
	v_or_b32_e32 v37, 2, v2
	s_nop 0
	v_cndmask_b32_e32 v21, v230, v21, vcc
	v_cmp_le_i32_e32 vcc, v37, v241
	v_or_b32_e32 v37, 34, v2
	s_nop 0
	v_cndmask_b32_e32 v6, v230, v6, vcc
	v_cmp_le_i32_e32 vcc, v37, v241
	v_or_b32_e32 v37, 3, v2
	s_nop 0
	v_cndmask_b32_e32 v22, v230, v22, vcc
	v_cmp_le_i32_e32 vcc, v37, v241
	v_or_b32_e32 v37, 35, v2
	s_nop 0
	v_cndmask_b32_e32 v7, v230, v7, vcc
	v_cmp_le_i32_e32 vcc, v37, v241
	v_or_b32_e32 v37, 8, v2
	s_nop 0
	v_cndmask_b32_e32 v23, v230, v23, vcc
	v_cmp_le_i32_e32 vcc, v37, v241
	v_or_b32_e32 v37, 40, v2
	s_nop 0
	v_cndmask_b32_e32 v8, v230, v8, vcc
	v_cmp_le_i32_e32 vcc, v37, v241
	v_or_b32_e32 v37, 9, v2
	s_nop 0
	v_cndmask_b32_e32 v24, v230, v24, vcc
	v_cmp_le_i32_e32 vcc, v37, v241
	v_or_b32_e32 v37, 41, v2
	s_nop 0
	v_cndmask_b32_e32 v9, v230, v9, vcc
	v_cmp_le_i32_e32 vcc, v37, v241
	v_or_b32_e32 v37, 10, v2
	s_nop 0
	v_cndmask_b32_e32 v25, v230, v25, vcc
	v_cmp_le_i32_e32 vcc, v37, v241
	v_or_b32_e32 v37, 42, v2
	s_nop 0
	v_cndmask_b32_e32 v10, v230, v10, vcc
	v_cmp_le_i32_e32 vcc, v37, v241
	v_or_b32_e32 v37, 11, v2
	s_nop 0
	v_cndmask_b32_e32 v26, v230, v26, vcc
	v_cmp_le_i32_e32 vcc, v37, v241
	v_or_b32_e32 v37, 43, v2
	s_nop 0
	v_cndmask_b32_e32 v11, v230, v11, vcc
	v_cmp_le_i32_e32 vcc, v37, v241
	v_or_b32_e32 v37, 16, v2
	s_nop 0
	v_cndmask_b32_e32 v27, v230, v27, vcc
	v_cmp_le_i32_e32 vcc, v37, v241
	v_or_b32_e32 v37, 48, v2
	s_nop 0
	v_cndmask_b32_e32 v12, v230, v12, vcc
	v_cmp_le_i32_e32 vcc, v37, v241
	v_or_b32_e32 v37, 17, v2
	s_nop 0
	v_cndmask_b32_e32 v28, v230, v28, vcc
	v_cmp_le_i32_e32 vcc, v37, v241
	v_or_b32_e32 v37, 49, v2
	s_nop 0
	v_cndmask_b32_e32 v13, v230, v13, vcc
	v_cmp_le_i32_e32 vcc, v37, v241
	v_or_b32_e32 v37, 18, v2
	s_nop 0
	v_cndmask_b32_e32 v29, v230, v29, vcc
	v_cmp_le_i32_e32 vcc, v37, v241
	v_or_b32_e32 v37, 50, v2
	s_nop 0
	v_cndmask_b32_e32 v14, v230, v14, vcc
	v_cmp_le_i32_e32 vcc, v37, v241
	v_or_b32_e32 v37, 19, v2
	s_nop 0
	v_cndmask_b32_e32 v30, v230, v30, vcc
	v_cmp_le_i32_e32 vcc, v37, v241
	v_or_b32_e32 v37, 51, v2
	s_nop 0
	v_cndmask_b32_e32 v15, v230, v15, vcc
	v_cmp_le_i32_e32 vcc, v37, v241
	v_or_b32_e32 v37, 24, v2
	s_nop 0
	v_cndmask_b32_e32 v31, v230, v31, vcc
	v_cmp_le_i32_e32 vcc, v37, v241
	v_or_b32_e32 v37, 56, v2
	s_nop 0
	v_cndmask_b32_e32 v16, v230, v16, vcc
	v_cmp_le_i32_e32 vcc, v37, v241
	v_or_b32_e32 v37, 25, v2
	s_nop 0
	v_cndmask_b32_e32 v32, v230, v32, vcc
	v_cmp_le_i32_e32 vcc, v37, v241
	v_or_b32_e32 v37, 57, v2
	s_nop 0
	v_cndmask_b32_e32 v17, v230, v17, vcc
	v_cmp_le_i32_e32 vcc, v37, v241
	v_or_b32_e32 v37, 26, v2
	s_nop 0
	v_cndmask_b32_e32 v33, v230, v33, vcc
	v_cmp_le_i32_e32 vcc, v37, v241
	v_or_b32_e32 v37, 58, v2
	s_nop 0
	v_cndmask_b32_e32 v18, v230, v18, vcc
	v_cmp_le_i32_e32 vcc, v37, v241
	v_or_b32_e32 v37, 27, v2
	v_or_b32_e32 v2, 59, v2
	v_cndmask_b32_e32 v34, v230, v34, vcc
	v_cmp_le_i32_e32 vcc, v37, v241
	s_nop 1
	v_cndmask_b32_e32 v19, v230, v19, vcc
	v_cmp_le_i32_e32 vcc, v2, v241
	s_nop 1
	v_cndmask_b32_e32 v35, v230, v35, vcc

.LBB0_346:
	s_waitcnt lgkmcnt(0)
	s_andn2_b64 vcc, exec, s[0:1]
	s_cbranch_vccnz .LBB0_299
	global_load_dword v44, v3, s[6:7]
	v_lshlrev_b32_e32 v102, 2, v2
	s_waitcnt lgkmcnt(3)
	v_lshlrev_b32_e32 v31, 16, v21
	v_lshlrev_b32_e32 v30, 16, v20
	v_and_b32_e32 v35, 0xffff0000, v21
	v_and_b32_e32 v34, 0xffff0000, v20
	v_lshlrev_b32_e32 v49, 16, v23
	v_lshlrev_b32_e32 v48, 16, v22
	v_and_b32_e32 v71, 0xffff0000, v23
	v_and_b32_e32 v70, 0xffff0000, v22
	global_load_dwordx4 v[20:23], v102, s[16:17] offset:16
	global_load_dwordx4 v[24:27], v102, s[16:17]
	v_and_b32_e32 v68, 64, v231
	v_xor_b32_e32 v45, 1, v231
	s_waitcnt vmcnt(7)
	v_lshlrev_b32_e32 v46, 16, v100
	v_and_b32_e32 v66, 0xffff0000, v100
	v_add_u32_e32 v100, 64, v68
	v_cmp_lt_i32_e32 vcc, v45, v100
	v_lshlrev_b32_e32 v29, 16, v99
	v_lshlrev_b32_e32 v28, 16, v98
	v_cndmask_b32_e32 v45, v231, v45, vcc
	v_and_b32_e32 v33, 0xffff0000, v99
	v_and_b32_e32 v32, 0xffff0000, v98
	v_and_b32_e32 v67, 0xffff0000, v101
	v_lshlrev_b32_e32 v74, 16, v97
	v_and_b32_e32 v75, 0xffff0000, v97
	v_lshlrev_b32_e32 v76, 16, v65
	v_and_b32_e32 v77, 0xffff0000, v65
	v_lshlrev_b32_e32 v78, 16, v96
	v_and_b32_e32 v79, 0xffff0000, v96
	v_lshlrev_b32_e32 v80, 16, v64
	v_and_b32_e32 v81, 0xffff0000, v64
	v_lshlrev_b32_e32 v64, 16, v95
	v_and_b32_e32 v65, 0xffff0000, v95
	v_lshlrev_b32_e32 v96, 16, v63
	v_and_b32_e32 v97, 0xffff0000, v63
	v_lshlrev_b32_e32 v98, 16, v94
	v_and_b32_e32 v99, 0xffff0000, v94
	v_lshlrev_b32_e32 v94, 16, v62
	v_and_b32_e32 v95, 0xffff0000, v62
	v_lshlrev_b32_e32 v45, 2, v45
	v_lshlrev_b32_e32 v47, 16, v101
	v_xor_b32_e32 v103, 2, v231
	v_cmp_lt_i32_e32 vcc, v103, v100
	v_xor_b32_e32 v104, 4, v231
	s_lshl_b64 s[0:1], s[40:41], 13
	s_add_u32 s0, s35, s0
	v_lshlrev_b32_e32 v2, 1, v2
	s_addc_u32 s1, s8, s1
	s_waitcnt vmcnt(2)
	v_pk_fma_f32 v[62:63], v[44:45], v[70:71], v[66:67] op_sel_hi:[0,1,1] neg_lo:[1,0,0] neg_hi:[1,0,0]
	v_pk_fma_f32 v[66:67], v[44:45], v[76:77], v[74:75] op_sel_hi:[0,1,1] neg_lo:[1,0,0] neg_hi:[1,0,0]
	v_pk_fma_f32 v[64:65], v[44:45], v[96:97], v[64:65] op_sel_hi:[0,1,1] neg_lo:[1,0,0] neg_hi:[1,0,0]
	v_pk_fma_f32 v[74:75], v[44:45], v[94:95], v[98:99] op_sel_hi:[0,1,1] neg_lo:[1,0,0] neg_hi:[1,0,0]
	v_pk_fma_f32 v[48:49], v[44:45], v[48:49], v[46:47] op_sel_hi:[0,1,1] neg_lo:[1,0,0] neg_hi:[1,0,0]
	v_pk_fma_f32 v[70:71], v[44:45], v[80:81], v[78:79] op_sel_hi:[0,1,1] neg_lo:[1,0,0] neg_hi:[1,0,0]
	v_pk_mul_f32 v[46:47], v[64:65], v[64:65]
	v_pk_mul_f32 v[76:77], v[74:75], v[74:75]
	v_pk_fma_f32 v[72:73], v[44:45], v[34:35], v[32:33] op_sel_hi:[0,1,1] neg_lo:[1,0,0] neg_hi:[1,0,0]
	v_pk_mul_f32 v[32:33], v[66:67], v[66:67]
	v_pk_mul_f32 v[34:35], v[70:71], v[70:71]
	v_add_f32_e32 v46, v46, v47
	v_add_f32_e32 v47, v76, v77
	v_add_f32_e32 v34, v34, v35
	v_add_f32_e32 v32, v32, v33
	v_add_f32_e32 v33, v47, v46
	v_pk_fma_f32 v[68:69], v[44:45], v[30:31], v[28:29] op_sel_hi:[0,1,1] neg_lo:[1,0,0] neg_hi:[1,0,0]
	v_pk_mul_f32 v[28:29], v[72:73], v[72:73]
	v_add_f32_e32 v33, v34, v33
	v_pk_fma_f32 v[28:29], v[68:69], v[68:69], v[28:29]
	v_add_f32_e32 v32, v32, v33
	v_pk_mul_f32 v[30:31], v[62:63], v[62:63]
	v_add_f32_e32 v28, v28, v32
	v_pk_fma_f32 v[30:31], v[48:49], v[48:49], v[30:31]
	v_add_f32_e32 v28, v29, v28
	v_add_f32_e32 v28, v30, v28
	v_add_f32_e32 v28, v31, v28
	ds_bpermute_b32 v29, v45, v28
	v_cndmask_b32_e32 v30, v231, v103, vcc
	v_lshlrev_b32_e32 v76, 2, v30
	v_cmp_lt_i32_e32 vcc, v104, v100
	v_lshlrev_b32_e32 v78, 10, v232
	s_waitcnt lgkmcnt(0)
	v_add_f32_e32 v28, v28, v29
	ds_bpermute_b32 v29, v76, v28
	v_cndmask_b32_e32 v30, v231, v104, vcc
	v_lshlrev_b32_e32 v77, 2, v30
	v_lshlrev_b32_e32 v79, 16, v91
	s_waitcnt lgkmcnt(0)
	v_add_f32_e32 v46, v28, v29
	global_load_dwordx4 v[28:31], v102, s[16:17] offset:272
	global_load_dwordx4 v[32:35], v102, s[16:17] offset:256
	ds_bpermute_b32 v47, v77, v46
	s_waitcnt lgkmcnt(0)
	v_add_f32_e32 v46, v46, v47
	v_fmamk_f32 v46, v46, 0x3c000000, v1
	v_mul_f32_e32 v47, 0x4f800000, v46
	v_cmp_gt_f32_e32 vcc, s88, v46
	s_nop 1
	v_cndmask_b32_e32 v80, v46, v47, vcc
	v_sqrt_f32_e32 v81, v80
	v_lshl_add_u64 v[46:47], s[0:1], 0, v[2:3]
	v_and_b32_e32 v2, 0xe000, v78
	v_lshl_add_u64 v[46:47], v[46:47], 0, v[2:3]
	v_add_u32_e32 v2, -1, v81
	v_add_u32_e32 v78, 1, v81
	v_fma_f32 v94, -v2, v81, v80
	v_fma_f32 v95, -v78, v81, v80
	v_cmp_ge_f32_e64 s[0:1], 0, v94
	s_nop 1
	v_cndmask_b32_e64 v2, v81, v2, s[0:1]
	v_cmp_lt_f32_e64 s[0:1], 0, v95
	s_nop 1
	v_cndmask_b32_e64 v2, v2, v78, s[0:1]
	v_mul_f32_e32 v78, 0x37800000, v2
	v_cndmask_b32_e32 v2, v2, v78, vcc
	v_cmp_class_f32_e32 vcc, v80, v223
	s_nop 1
	v_cndmask_b32_e32 v2, v2, v80, vcc
	v_div_scale_f32 v78, s[0:1], v2, v2, s89
	v_rcp_f32_e32 v81, v78
	v_mov_b32_e32 v80, v68
	v_div_scale_f32 v68, vcc, s89, v2, s89
	v_fma_f32 v94, -v78, v81, 1.0
	v_fmac_f32_e32 v81, v94, v81
	v_mul_f32_e32 v94, v68, v81
	v_fma_f32 v95, -v78, v94, v68
	v_fmac_f32_e32 v94, v95, v81
	v_fma_f32 v68, -v78, v94, v68
	v_div_fmas_f32 v68, v68, v81, v94
	v_div_fixup_f32 v2, v68, v2, s89
	v_pk_mul_f32 v[74:75], v[74:75], v[2:3] op_sel_hi:[1,0]
	v_pk_mul_f32 v[64:65], v[64:65], v[2:3] op_sel_hi:[1,0]
	v_pk_mul_f32 v[70:71], v[70:71], v[2:3] op_sel_hi:[1,0]
	v_pk_mul_f32 v[66:67], v[66:67], v[2:3] op_sel_hi:[1,0]
	s_waitcnt vmcnt(2)
	v_pk_mul_f32 v[74:75], v[24:25], v[74:75]
	v_pk_mul_f32 v[94:95], v[26:27], v[64:65]
	v_pk_mul_f32 v[70:71], v[20:21], v[70:71]
	v_pk_mul_f32 v[96:97], v[22:23], v[66:67]
	v_cvt_pk_bf16_f32 v64, v74, v75
	v_cvt_pk_bf16_f32 v65, v94, v95
	v_cvt_pk_bf16_f32 v66, v70, v71
	v_cvt_pk_bf16_f32 v67, v96, v97
	global_store_dwordx4 v[46:47], v[64:67], off nt
	v_lshlrev_b32_e32 v78, 16, v90
	v_lshlrev_b32_e32 v75, 16, v43
	v_lshlrev_b32_e32 v65, 16, v41
	v_lshlrev_b32_e32 v64, 16, v40
	v_and_b32_e32 v67, 0xffff0000, v91
	v_and_b32_e32 v66, 0xffff0000, v90
	v_and_b32_e32 v41, 0xffff0000, v41
	v_and_b32_e32 v40, 0xffff0000, v40
	v_pk_fma_f32 v[70:71], v[44:45], v[40:41], v[66:67] op_sel_hi:[0,1,1] neg_lo:[1,0,0] neg_hi:[1,0,0]
	v_lshlrev_b32_e32 v67, 16, v93
	v_lshlrev_b32_e32 v66, 16, v92
	v_lshlrev_b32_e32 v74, 16, v42
	v_pk_fma_f32 v[64:65], v[44:45], v[64:65], v[78:79] op_sel_hi:[0,1,1] neg_lo:[1,0,0] neg_hi:[1,0,0]
	v_pk_fma_f32 v[66:67], v[44:45], v[74:75], v[66:67] op_sel_hi:[0,1,1] neg_lo:[1,0,0] neg_hi:[1,0,0]
	v_and_b32_e32 v75, 0xffff0000, v93
	v_and_b32_e32 v74, 0xffff0000, v92
	v_lshlrev_b32_e32 v78, 16, v89
	v_and_b32_e32 v79, 0xffff0000, v89
	v_lshlrev_b32_e32 v92, 16, v88
	v_and_b32_e32 v93, 0xffff0000, v88
	v_lshlrev_b32_e32 v88, 16, v60
	v_and_b32_e32 v89, 0xffff0000, v60
	v_lshlrev_b32_e32 v90, 16, v61
	v_and_b32_e32 v91, 0xffff0000, v61
	v_pk_fma_f32 v[60:61], v[44:45], v[88:89], v[92:93] op_sel_hi:[0,1,1] neg_lo:[1,0,0] neg_hi:[1,0,0]
	v_lshlrev_b32_e32 v92, 16, v87
	v_and_b32_e32 v93, 0xffff0000, v87
	v_lshlrev_b32_e32 v94, 16, v59
	v_and_b32_e32 v95, 0xffff0000, v59
	v_lshlrev_b32_e32 v96, 16, v86
	v_and_b32_e32 v97, 0xffff0000, v86
	v_lshlrev_b32_e32 v86, 16, v58
	v_and_b32_e32 v87, 0xffff0000, v58
	v_pk_fma_f32 v[92:93], v[44:45], v[94:95], v[92:93] op_sel_hi:[0,1,1] neg_lo:[1,0,0] neg_hi:[1,0,0]
	v_pk_fma_f32 v[58:59], v[44:45], v[86:87], v[96:97] op_sel_hi:[0,1,1] neg_lo:[1,0,0] neg_hi:[1,0,0]
	v_pk_mul_f32 v[94:95], v[92:93], v[92:93]
	v_pk_mul_f32 v[86:87], v[58:59], v[58:59]
	v_pk_fma_f32 v[78:79], v[44:45], v[90:91], v[78:79] op_sel_hi:[0,1,1] neg_lo:[1,0,0] neg_hi:[1,0,0]
	v_pk_mul_f32 v[88:89], v[60:61], v[60:61]
	v_add_f32_e32 v68, v94, v95
	v_add_f32_e32 v81, v86, v87
	v_pk_mul_f32 v[90:91], v[78:79], v[78:79]
	v_add_f32_e32 v68, v81, v68
	v_add_f32_e32 v81, v88, v89
	v_pk_mul_f32 v[40:41], v[70:71], v[70:71]
	v_and_b32_e32 v43, 0xffff0000, v43
	v_and_b32_e32 v42, 0xffff0000, v42
	v_add_f32_e32 v68, v81, v68
	v_add_f32_e32 v81, v90, v91
	v_pk_fma_f32 v[40:41], v[64:65], v[64:65], v[40:41]
	v_pk_fma_f32 v[74:75], v[44:45], v[42:43], v[74:75] op_sel_hi:[0,1,1] neg_lo:[1,0,0] neg_hi:[1,0,0]
	v_add_f32_e32 v68, v81, v68
	v_pk_mul_f32 v[42:43], v[74:75], v[74:75]
	v_add_f32_e32 v40, v40, v68
	v_pk_fma_f32 v[42:43], v[66:67], v[66:67], v[42:43]
	v_add_f32_e32 v40, v41, v40
	v_add_f32_e32 v40, v42, v40
	v_add_f32_e32 v42, v43, v40
	ds_bpermute_b32 v43, v45, v42
	v_mov_b32_e32 v81, v72
	v_pk_mul_f32 v[40:41], v[80:81], v[2:3] op_sel_hi:[1,0]
	v_mov_b32_e32 v72, v69
	s_waitcnt vmcnt(1)
	v_pk_mul_f32 v[40:41], v[32:33], v[40:41]
	s_waitcnt lgkmcnt(0)
	v_add_f32_e32 v68, v42, v43
	ds_bpermute_b32 v80, v76, v68
	v_pk_mul_f32 v[42:43], v[72:73], v[2:3] op_sel_hi:[1,0]
	v_cvt_pk_bf16_f32 v40, v40, v41
	v_pk_mul_f32 v[42:43], v[34:35], v[42:43]
	v_lshlrev_b32_e32 v72, 16, v57
	s_waitcnt lgkmcnt(0)
	v_add_f32_e32 v68, v68, v80
	ds_bpermute_b32 v69, v77, v68
	v_cvt_pk_bf16_f32 v41, v42, v43
	v_mov_b32_e32 v42, v48
	v_mov_b32_e32 v43, v62
	v_pk_mul_f32 v[42:43], v[42:43], v[2:3] op_sel_hi:[1,0]
	s_waitcnt lgkmcnt(0)
	v_add_f32_e32 v48, v68, v69
	v_fmamk_f32 v48, v48, 0x3c000000, v1
	v_mul_f32_e32 v62, 0x4f800000, v48
	v_cmp_gt_f32_e32 vcc, s88, v48
	v_pk_mul_f32 v[42:43], v[28:29], v[42:43]
	v_and_b32_e32 v73, 0xffff0000, v57
	v_cndmask_b32_e32 v68, v48, v62, vcc
	v_sqrt_f32_e32 v69, v68
	v_mov_b32_e32 v62, v49
	v_pk_mul_f32 v[48:49], v[62:63], v[2:3] op_sel_hi:[1,0]
	v_cvt_pk_bf16_f32 v42, v42, v43
	v_add_u32_e32 v2, -1, v69
	v_fma_f32 v43, -v2, v69, v68
	v_cmp_ge_f32_e64 s[0:1], 0, v43
	v_add_u32_e32 v43, 1, v69
	v_fma_f32 v62, -v43, v69, v68
	v_cndmask_b32_e64 v2, v69, v2, s[0:1]
	v_cmp_lt_f32_e64 s[0:1], 0, v62
	v_pk_mul_f32 v[48:49], v[30:31], v[48:49]
	v_and_b32_e32 v69, 0xffff0000, v15
	v_cndmask_b32_e64 v2, v2, v43, s[0:1]
	v_mul_f32_e32 v43, 0x37800000, v2
	v_cndmask_b32_e32 v2, v2, v43, vcc
	v_cmp_class_f32_e32 vcc, v68, v223
	v_cvt_pk_bf16_f32 v43, v48, v49
	global_store_dwordx4 v[46:47], v[40:43], off offset:128 nt
	v_cndmask_b32_e32 v2, v2, v68, vcc
	v_div_scale_f32 v62, s[0:1], v2, v2, s89
	v_rcp_f32_e32 v63, v62
	s_mov_b32 s0, 0x10000
	v_lshlrev_b32_e32 v68, 16, v15
	v_and_b32_e32 v15, 0xffff0000, v56
	v_fma_f32 v40, -v62, v63, 1.0
	v_fmac_f32_e32 v63, v40, v63
	v_div_scale_f32 v40, vcc, s89, v2, s89
	v_mul_f32_e32 v41, v40, v63
	v_fma_f32 v42, -v62, v41, v40
	v_fmac_f32_e32 v41, v42, v63
	v_fma_f32 v40, -v62, v41, v40
	v_div_fmas_f32 v40, v40, v63, v41
	v_div_fixup_f32 v2, v40, v2, s89
	v_pk_mul_f32 v[40:41], v[58:59], v[2:3] op_sel_hi:[1,0]
	v_pk_mul_f32 v[42:43], v[92:93], v[2:3] op_sel_hi:[1,0]
	v_pk_mul_f32 v[40:41], v[24:25], v[40:41]
	v_pk_mul_f32 v[42:43], v[26:27], v[42:43]
	v_cvt_pk_bf16_f32 v40, v40, v41
	v_cvt_pk_bf16_f32 v41, v42, v43
	v_pk_mul_f32 v[42:43], v[60:61], v[2:3] op_sel_hi:[1,0]
	v_pk_mul_f32 v[48:49], v[78:79], v[2:3] op_sel_hi:[1,0]
	v_pk_mul_f32 v[42:43], v[20:21], v[42:43]
	v_pk_mul_f32 v[48:49], v[22:23], v[48:49]
	v_cvt_pk_bf16_f32 v42, v42, v43
	v_cvt_pk_bf16_f32 v43, v48, v49
	v_add_co_u32_e32 v48, vcc, s0, v46
	v_lshlrev_b32_e32 v78, 16, v14
	s_nop 0
	v_addc_co_u32_e32 v49, vcc, 0, v47, vcc
	global_store_dwordx4 v[48:49], v[40:43], off nt
	v_and_b32_e32 v79, 0xffff0000, v14
	v_lshlrev_b32_e32 v14, 16, v56
	v_lshlrev_b32_e32 v41, 16, v83
	v_lshlrev_b32_e32 v40, 16, v82
	v_lshlrev_b32_e32 v43, 16, v37
	v_lshlrev_b32_e32 v42, 16, v36
	v_pk_fma_f32 v[40:41], v[44:45], v[42:43], v[40:41] op_sel_hi:[0,1,1] neg_lo:[1,0,0] neg_hi:[1,0,0]
	v_and_b32_e32 v43, 0xffff0000, v83
	v_and_b32_e32 v42, 0xffff0000, v82
	v_pk_fma_f32 v[56:57], v[44:45], v[14:15], v[78:79] op_sel_hi:[0,1,1] neg_lo:[1,0,0] neg_hi:[1,0,0]
	v_lshlrev_b32_e32 v78, 16, v13
	v_and_b32_e32 v79, 0xffff0000, v13
	v_lshlrev_b32_e32 v80, 16, v55
	v_and_b32_e32 v81, 0xffff0000, v55
	v_lshlrev_b32_e32 v82, 16, v12
	v_and_b32_e32 v83, 0xffff0000, v12
	v_lshlrev_b32_e32 v12, 16, v54
	v_and_b32_e32 v13, 0xffff0000, v54
	v_and_b32_e32 v37, 0xffff0000, v37
	v_and_b32_e32 v36, 0xffff0000, v36
	v_pk_fma_f32 v[78:79], v[44:45], v[80:81], v[78:79] op_sel_hi:[0,1,1] neg_lo:[1,0,0] neg_hi:[1,0,0]
	v_pk_fma_f32 v[54:55], v[44:45], v[12:13], v[82:83] op_sel_hi:[0,1,1] neg_lo:[1,0,0] neg_hi:[1,0,0]
	v_pk_fma_f32 v[42:43], v[44:45], v[36:37], v[42:43] op_sel_hi:[0,1,1] neg_lo:[1,0,0] neg_hi:[1,0,0]
	v_pk_mul_f32 v[80:81], v[78:79], v[78:79]
	v_pk_mul_f32 v[12:13], v[54:55], v[54:55]
	v_pk_mul_f32 v[36:37], v[42:43], v[42:43]
	v_pk_fma_f32 v[68:69], v[44:45], v[72:73], v[68:69] op_sel_hi:[0,1,1] neg_lo:[1,0,0] neg_hi:[1,0,0]
	v_pk_mul_f32 v[14:15], v[56:57], v[56:57]
	v_add_f32_e32 v59, v80, v81
	v_add_f32_e32 v12, v12, v13
	v_pk_fma_f32 v[60:61], v[40:41], v[40:41], v[36:37]
	v_lshlrev_b32_e32 v37, 16, v85
	v_lshlrev_b32_e32 v36, 16, v84
	v_lshlrev_b32_e32 v63, 16, v39
	v_lshlrev_b32_e32 v62, 16, v38
	v_pk_mul_f32 v[72:73], v[68:69], v[68:69]
	v_add_f32_e32 v12, v12, v59
	v_add_f32_e32 v13, v14, v15
	v_pk_fma_f32 v[36:37], v[44:45], v[62:63], v[36:37] op_sel_hi:[0,1,1] neg_lo:[1,0,0] neg_hi:[1,0,0]
	v_and_b32_e32 v63, 0xffff0000, v85
	v_and_b32_e32 v62, 0xffff0000, v84
	v_and_b32_e32 v39, 0xffff0000, v39
	v_and_b32_e32 v38, 0xffff0000, v38
	v_add_f32_e32 v12, v13, v12
	v_add_f32_e32 v13, v72, v73
	v_pk_fma_f32 v[38:39], v[44:45], v[38:39], v[62:63] op_sel_hi:[0,1,1] neg_lo:[1,0,0] neg_hi:[1,0,0]
	v_add_f32_e32 v12, v13, v12
	v_pk_mul_f32 v[62:63], v[38:39], v[38:39]
	v_add_f32_e32 v12, v60, v12
	v_pk_fma_f32 v[62:63], v[36:37], v[36:37], v[62:63]
	v_add_f32_e32 v12, v61, v12
	v_add_f32_e32 v12, v62, v12
	v_add_f32_e32 v14, v63, v12
	ds_bpermute_b32 v15, v45, v14
	v_mov_b32_e32 v58, v64
	v_mov_b32_e32 v59, v70
	v_pk_mul_f32 v[12:13], v[58:59], v[2:3] op_sel_hi:[1,0]
	v_mov_b32_e32 v70, v65
	s_waitcnt lgkmcnt(0)
	v_add_f32_e32 v58, v14, v15
	ds_bpermute_b32 v59, v76, v58
	v_pk_mul_f32 v[14:15], v[70:71], v[2:3] op_sel_hi:[1,0]
	v_pk_mul_f32 v[12:13], v[32:33], v[12:13]
	v_pk_mul_f32 v[14:15], v[34:35], v[14:15]
	v_cvt_pk_bf16_f32 v12, v12, v13
	s_waitcnt lgkmcnt(0)
	v_add_f32_e32 v58, v58, v59
	ds_bpermute_b32 v59, v77, v58
	v_cvt_pk_bf16_f32 v13, v14, v15
	v_mov_b32_e32 v14, v66
	v_mov_b32_e32 v15, v74
	v_pk_mul_f32 v[14:15], v[14:15], v[2:3] op_sel_hi:[1,0]
	s_waitcnt lgkmcnt(0)
	v_add_f32_e32 v58, v58, v59
	v_fmamk_f32 v58, v58, 0x3c000000, v1
	v_mul_f32_e32 v59, 0x4f800000, v58
	v_cmp_gt_f32_e32 vcc, s88, v58
	v_mov_b32_e32 v74, v67
	v_pk_mul_f32 v[14:15], v[28:29], v[14:15]
	v_cndmask_b32_e32 v60, v58, v59, vcc
	v_sqrt_f32_e32 v61, v60
	v_pk_mul_f32 v[58:59], v[74:75], v[2:3] op_sel_hi:[1,0]
	v_cvt_pk_bf16_f32 v14, v14, v15
	v_pk_mul_f32 v[58:59], v[30:31], v[58:59]
	v_add_u32_e32 v2, -1, v61
	v_fma_f32 v15, -v2, v61, v60
	v_cmp_ge_f32_e64 s[0:1], 0, v15
	v_add_u32_e32 v15, 1, v61
	v_lshlrev_b32_e32 v62, 16, v51
	v_cndmask_b32_e64 v2, v61, v2, s[0:1]
	v_fma_f32 v61, -v15, v61, v60
	v_cmp_lt_f32_e64 s[0:1], 0, v61
	v_and_b32_e32 v63, 0xffff0000, v51
	v_lshlrev_b32_e32 v64, 16, v4
	v_cndmask_b32_e64 v2, v2, v15, s[0:1]
	v_mul_f32_e32 v15, 0x37800000, v2
	v_cndmask_b32_e32 v2, v2, v15, vcc
	v_cmp_class_f32_e32 vcc, v60, v223
	v_cvt_pk_bf16_f32 v15, v58, v59
	global_store_dwordx4 v[48:49], v[12:15], off offset:128 nt
	v_cndmask_b32_e32 v2, v2, v60, vcc
	v_div_scale_f32 v60, s[0:1], v2, v2, s89
	v_rcp_f32_e32 v61, v60
	s_mov_b32 s0, 0x20000
	v_lshlrev_b32_e32 v58, 16, v53
	v_and_b32_e32 v59, 0xffff0000, v53
	v_fma_f32 v12, -v60, v61, 1.0
	v_fmac_f32_e32 v61, v12, v61
	v_div_scale_f32 v12, vcc, s89, v2, s89
	v_mul_f32_e32 v13, v12, v61
	v_fma_f32 v14, -v60, v13, v12
	v_fmac_f32_e32 v13, v14, v61
	v_fma_f32 v12, -v60, v13, v12
	v_div_fmas_f32 v12, v12, v61, v13
	v_div_fixup_f32 v2, v12, v2, s89
	v_pk_mul_f32 v[12:13], v[54:55], v[2:3] op_sel_hi:[1,0]
	v_pk_mul_f32 v[14:15], v[78:79], v[2:3] op_sel_hi:[1,0]
	v_pk_mul_f32 v[12:13], v[24:25], v[12:13]
	v_pk_mul_f32 v[14:15], v[26:27], v[14:15]
	v_cvt_pk_bf16_f32 v12, v12, v13
	v_cvt_pk_bf16_f32 v13, v14, v15
	v_pk_mul_f32 v[14:15], v[56:57], v[2:3] op_sel_hi:[1,0]
	v_pk_mul_f32 v[48:49], v[68:69], v[2:3] op_sel_hi:[1,0]
	v_pk_mul_f32 v[14:15], v[20:21], v[14:15]
	v_pk_mul_f32 v[48:49], v[22:23], v[48:49]
	v_cvt_pk_bf16_f32 v14, v14, v15
	v_cvt_pk_bf16_f32 v15, v48, v49
	v_add_co_u32_e32 v48, vcc, s0, v46
	v_lshlrev_b32_e32 v55, 16, v17
	s_nop 0
	v_addc_co_u32_e32 v49, vcc, 0, v47, vcc
	global_store_dwordx4 v[48:49], v[12:15], off nt
	v_lshlrev_b32_e32 v54, 16, v16
	v_lshlrev_b32_e32 v57, 16, v19
	v_lshlrev_b32_e32 v15, 16, v9
	v_lshlrev_b32_e32 v14, 16, v8
	v_pk_fma_f32 v[14:15], v[44:45], v[54:55], v[14:15] op_sel_hi:[0,1,1] neg_lo:[1,0,0] neg_hi:[1,0,0]
	v_lshlrev_b32_e32 v55, 16, v11
	v_lshlrev_b32_e32 v54, 16, v10
	v_lshlrev_b32_e32 v56, 16, v18
	v_pk_fma_f32 v[54:55], v[44:45], v[56:57], v[54:55] op_sel_hi:[0,1,1] neg_lo:[1,0,0] neg_hi:[1,0,0]
	v_lshlrev_b32_e32 v56, 16, v7
	v_and_b32_e32 v57, 0xffff0000, v7
	v_lshlrev_b32_e32 v60, 16, v6
	v_and_b32_e32 v61, 0xffff0000, v6
	v_lshlrev_b32_e32 v6, 16, v52
	v_and_b32_e32 v7, 0xffff0000, v52
	v_pk_fma_f32 v[52:53], v[44:45], v[6:7], v[60:61] op_sel_hi:[0,1,1] neg_lo:[1,0,0] neg_hi:[1,0,0]
	v_lshlrev_b32_e32 v60, 16, v5
	v_and_b32_e32 v61, 0xffff0000, v5
	v_and_b32_e32 v65, 0xffff0000, v4
	v_lshlrev_b32_e32 v4, 16, v50
	v_and_b32_e32 v5, 0xffff0000, v50
	v_pk_fma_f32 v[60:61], v[44:45], v[62:63], v[60:61] op_sel_hi:[0,1,1] neg_lo:[1,0,0] neg_hi:[1,0,0]
	v_pk_fma_f32 v[50:51], v[44:45], v[4:5], v[64:65] op_sel_hi:[0,1,1] neg_lo:[1,0,0] neg_hi:[1,0,0]
	v_pk_mul_f32 v[62:63], v[60:61], v[60:61]
	v_pk_mul_f32 v[4:5], v[50:51], v[50:51]
	v_and_b32_e32 v9, 0xffff0000, v9
	v_and_b32_e32 v8, 0xffff0000, v8
	v_and_b32_e32 v17, 0xffff0000, v17
	v_and_b32_e32 v16, 0xffff0000, v16
	v_pk_fma_f32 v[56:57], v[44:45], v[58:59], v[56:57] op_sel_hi:[0,1,1] neg_lo:[1,0,0] neg_hi:[1,0,0]
	v_pk_mul_f32 v[6:7], v[52:53], v[52:53]
	v_add_f32_e32 v13, v62, v63
	v_add_f32_e32 v4, v4, v5
	v_pk_fma_f32 v[8:9], v[44:45], v[16:17], v[8:9] op_sel_hi:[0,1,1] neg_lo:[1,0,0] neg_hi:[1,0,0]
	v_pk_mul_f32 v[58:59], v[56:57], v[56:57]
	v_add_f32_e32 v4, v4, v13
	v_add_f32_e32 v5, v6, v7
	v_pk_mul_f32 v[16:17], v[8:9], v[8:9]
	v_and_b32_e32 v11, 0xffff0000, v11
	v_and_b32_e32 v10, 0xffff0000, v10
	v_and_b32_e32 v19, 0xffff0000, v19
	v_and_b32_e32 v18, 0xffff0000, v18
	v_add_f32_e32 v4, v5, v4
	v_add_f32_e32 v5, v58, v59
	v_pk_fma_f32 v[16:17], v[14:15], v[14:15], v[16:17]
	v_pk_fma_f32 v[10:11], v[44:45], v[18:19], v[10:11] op_sel_hi:[0,1,1] neg_lo:[1,0,0] neg_hi:[1,0,0]
	v_add_f32_e32 v4, v5, v4
	v_pk_mul_f32 v[18:19], v[10:11], v[10:11]
	v_add_f32_e32 v4, v16, v4
	v_pk_fma_f32 v[18:19], v[54:55], v[54:55], v[18:19]
	v_add_f32_e32 v4, v17, v4
	v_add_f32_e32 v4, v18, v4
	v_add_f32_e32 v6, v19, v4
	ds_bpermute_b32 v7, v45, v6
	v_mov_b32_e32 v12, v40
	v_mov_b32_e32 v13, v42
	v_pk_mul_f32 v[4:5], v[12:13], v[2:3] op_sel_hi:[1,0]
	v_mov_b32_e32 v42, v41
	s_waitcnt lgkmcnt(0)
	v_add_f32_e32 v12, v6, v7
	ds_bpermute_b32 v13, v76, v12
	v_pk_mul_f32 v[6:7], v[42:43], v[2:3] op_sel_hi:[1,0]
	v_pk_mul_f32 v[4:5], v[32:33], v[4:5]
	v_pk_mul_f32 v[6:7], v[34:35], v[6:7]
	v_cvt_pk_bf16_f32 v4, v4, v5
	s_waitcnt lgkmcnt(0)
	v_add_f32_e32 v12, v12, v13
	ds_bpermute_b32 v13, v77, v12
	v_cvt_pk_bf16_f32 v5, v6, v7
	v_mov_b32_e32 v6, v36
	v_mov_b32_e32 v7, v38
	v_pk_mul_f32 v[6:7], v[6:7], v[2:3] op_sel_hi:[1,0]
	s_waitcnt lgkmcnt(0)
	v_add_f32_e32 v12, v12, v13
	v_fmamk_f32 v12, v12, 0x3c000000, v1
	v_mul_f32_e32 v13, 0x4f800000, v12
	v_cmp_gt_f32_e32 vcc, s88, v12
	v_mov_b32_e32 v38, v37
	v_pk_mul_f32 v[6:7], v[28:29], v[6:7]
	v_cndmask_b32_e32 v16, v12, v13, vcc
	v_sqrt_f32_e32 v17, v16
	v_pk_mul_f32 v[12:13], v[38:39], v[2:3] op_sel_hi:[1,0]
	v_cvt_pk_bf16_f32 v6, v6, v7
	v_pk_mul_f32 v[12:13], v[30:31], v[12:13]
	v_add_u32_e32 v2, -1, v17
	v_fma_f32 v7, -v2, v17, v16
	v_cmp_ge_f32_e64 s[0:1], 0, v7
	v_add_u32_e32 v7, 1, v17
	s_nop 0
	v_cndmask_b32_e64 v2, v17, v2, s[0:1]
	v_fma_f32 v17, -v7, v17, v16
	v_cmp_lt_f32_e64 s[0:1], 0, v17
	s_nop 1
	v_cndmask_b32_e64 v2, v2, v7, s[0:1]
	v_mul_f32_e32 v7, 0x37800000, v2
	v_cndmask_b32_e32 v2, v2, v7, vcc
	v_cmp_class_f32_e32 vcc, v16, v223
	v_cvt_pk_bf16_f32 v7, v12, v13
	global_store_dwordx4 v[48:49], v[4:7], off offset:128 nt
	v_cndmask_b32_e32 v2, v2, v16, vcc
	v_div_scale_f32 v16, s[0:1], v2, v2, s89
	v_rcp_f32_e32 v17, v16
	s_mov_b32 s0, 0x30000
	v_fma_f32 v4, -v16, v17, 1.0
	v_fmac_f32_e32 v17, v4, v17
	v_div_scale_f32 v4, vcc, s89, v2, s89
	v_mul_f32_e32 v5, v4, v17
	v_fma_f32 v6, -v16, v5, v4
	v_fmac_f32_e32 v5, v6, v17
	v_fma_f32 v4, -v16, v5, v4
	v_div_fmas_f32 v4, v4, v17, v5
	v_div_fixup_f32 v2, v4, v2, s89
	v_pk_mul_f32 v[4:5], v[50:51], v[2:3] op_sel_hi:[1,0]
	v_pk_mul_f32 v[6:7], v[60:61], v[2:3] op_sel_hi:[1,0]
	v_pk_mul_f32 v[4:5], v[24:25], v[4:5]
	v_pk_mul_f32 v[6:7], v[26:27], v[6:7]
	v_cvt_pk_bf16_f32 v4, v4, v5
	v_cvt_pk_bf16_f32 v5, v6, v7
	v_pk_mul_f32 v[6:7], v[52:53], v[2:3] op_sel_hi:[1,0]
	v_pk_mul_f32 v[12:13], v[56:57], v[2:3] op_sel_hi:[1,0]
	v_pk_mul_f32 v[6:7], v[20:21], v[6:7]
	v_pk_mul_f32 v[12:13], v[22:23], v[12:13]
	v_cvt_pk_bf16_f32 v6, v6, v7
	v_cvt_pk_bf16_f32 v7, v12, v13
	v_add_co_u32_e32 v12, vcc, s0, v46
	s_nop 1
	v_addc_co_u32_e32 v13, vcc, 0, v47, vcc
	global_store_dwordx4 v[12:13], v[4:7], off nt
	s_nop 1
	v_mov_b32_e32 v4, v14
	v_mov_b32_e32 v5, v8
	v_mov_b32_e32 v8, v15
	v_pk_mul_f32 v[4:5], v[4:5], v[2:3] op_sel_hi:[1,0]
	v_pk_mul_f32 v[6:7], v[8:9], v[2:3] op_sel_hi:[1,0]
	v_pk_mul_f32 v[4:5], v[32:33], v[4:5]
	v_pk_mul_f32 v[6:7], v[34:35], v[6:7]
	v_cvt_pk_bf16_f32 v4, v4, v5
	v_cvt_pk_bf16_f32 v5, v6, v7
	v_mov_b32_e32 v6, v54
	v_mov_b32_e32 v7, v10
	v_mov_b32_e32 v10, v55
	v_pk_mul_f32 v[6:7], v[6:7], v[2:3] op_sel_hi:[1,0]
	v_pk_mul_f32 v[8:9], v[10:11], v[2:3] op_sel_hi:[1,0]
	v_pk_mul_f32 v[6:7], v[28:29], v[6:7]
	v_pk_mul_f32 v[8:9], v[30:31], v[8:9]
	v_cvt_pk_bf16_f32 v6, v6, v7
	v_cvt_pk_bf16_f32 v7, v8, v9
	global_store_dwordx4 v[12:13], v[4:7], off offset:128 nt
	s_branch .LBB0_299

.LBB0_405:
	global_load_dwordx4 v[174:177], v[188:189], off
	global_load_dwordx4 v[178:181], v[190:191], off
	global_load_dwordx4 v[182:185], v[192:193], off
	global_load_dwordx4 v[162:165], v[188:189], off offset:16
	global_load_dwordx4 v[170:173], v[190:191], off offset:16
	global_load_dwordx4 v[166:169], v[192:193], off offset:16
	v_add_co_u32_e32 v4, vcc, 0x24600000, v2
	s_waitcnt vmcnt(30)
	v_lshlrev_b32_e32 v219, 16, v147
	v_addc_co_u32_e32 v5, vcc, 0, v3, vcc
	v_add_co_u32_e32 v6, vcc, 0x22600000, v2
	v_lshlrev_b32_e32 v218, 16, v146
	s_nop 0
	v_addc_co_u32_e32 v7, vcc, 0, v3, vcc
	s_waitcnt vmcnt(29)
	v_lshlrev_b32_e32 v215, 16, v159
	v_lshlrev_b32_e32 v214, 16, v158
	v_and_b32_e32 v213, 0xffff0000, v159
	v_and_b32_e32 v212, 0xffff0000, v158
	v_add_co_u32_e32 v8, vcc, 0x24601000, v2
	v_lshlrev_b32_e32 v217, 16, v151
	v_lshlrev_b32_e32 v216, 16, v150
	v_and_b32_e32 v221, 0xffff0000, v147
	v_and_b32_e32 v220, 0xffff0000, v146
	s_waitcnt vmcnt(28)
	v_lshlrev_b32_e32 v147, 16, v155
	v_lshlrev_b32_e32 v146, 16, v154
	v_and_b32_e32 v225, 0xffff0000, v155
	v_and_b32_e32 v224, 0xffff0000, v154
	v_addc_co_u32_e32 v9, vcc, 0, v3, vcc
	v_and_b32_e32 v151, 0xffff0000, v151
	v_and_b32_e32 v150, 0xffff0000, v150
	global_load_dwordx4 v[46:49], v[4:5], off offset:3072 nt
	global_load_dwordx4 v[42:45], v[6:7], off offset:3072 nt
	v_add_co_u32_e32 v4, vcc, 0x22601000, v2
	s_add_i32 s0, s0, s4
	s_nop 0
	v_addc_co_u32_e32 v5, vcc, 0, v3, vcc
	v_add_co_u32_e32 v6, vcc, 0x24602000, v2
	global_load_dwordx4 v[30:33], v[8:9], off offset:3072 nt
	global_load_dwordx4 v[26:29], v[4:5], off offset:3072 nt
	v_addc_co_u32_e32 v7, vcc, 0, v3, vcc
	v_add_co_u32_e32 v4, vcc, 0x22602000, v2
	s_waitcnt vmcnt(9)
	v_mov_b32_e32 v154, v174
	s_waitcnt vmcnt(8)
	v_mov_b32_e32 v158, v178
	v_mov_b32_e32 v159, v180
	v_mov_b32_e32 v155, v176
	v_mov_b32_e32 v176, v175
	v_mov_b32_e32 v180, v179
	v_pk_mul_f32 v[174:175], v[158:159], v[218:219]
	s_waitcnt vmcnt(7)
	v_mov_b32_e32 v210, v182
	v_mov_b32_e32 v211, v184
	v_pk_mul_f32 v[178:179], v[180:181], v[220:221]
	v_pk_fma_f32 v[174:175], v[154:155], v[216:217], v[174:175]
	v_mov_b32_e32 v184, v183
	v_pk_fma_f32 v[150:151], v[176:177], v[150:151], v[178:179]
	v_pk_fma_f32 v[174:175], v[210:211], v[214:215], v[174:175]
	v_lshlrev_b32_e32 v179, 16, v149
	v_lshlrev_b32_e32 v178, 16, v148
	v_and_b32_e32 v183, 0xffff0000, v149
	v_and_b32_e32 v182, 0xffff0000, v148
	s_waitcnt vmcnt(5)
	v_mov_b32_e32 v226, v170
	v_mov_b32_e32 v227, v172
	v_mov_b32_e32 v172, v171
	v_pk_mul_f32 v[146:147], v[174:175], v[146:147]
	v_lshlrev_b32_e32 v175, 16, v153
	v_lshlrev_b32_e32 v174, 16, v152
	v_and_b32_e32 v153, 0xffff0000, v153
	v_and_b32_e32 v152, 0xffff0000, v152
	v_mov_b32_e32 v148, v162
	v_mov_b32_e32 v149, v164
	v_pk_mul_f32 v[228:229], v[226:227], v[178:179]
	v_mov_b32_e32 v164, v163
	v_pk_mul_f32 v[162:163], v[172:173], v[182:183]
	v_pk_fma_f32 v[150:151], v[184:185], v[212:213], v[150:151]
	v_lshlrev_b32_e32 v217, 16, v161
	v_lshlrev_b32_e32 v216, 16, v160
	v_and_b32_e32 v161, 0xffff0000, v161
	v_and_b32_e32 v160, 0xffff0000, v160
	v_pk_fma_f32 v[174:175], v[148:149], v[174:175], v[228:229]
	s_waitcnt vmcnt(4)
	v_mov_b32_e32 v228, v166
	v_mov_b32_e32 v229, v168
	v_pk_fma_f32 v[152:153], v[164:165], v[152:153], v[162:163]
	v_mov_b32_e32 v168, v167
	v_pk_mul_f32 v[150:151], v[150:151], v[224:225]
	v_lshlrev_b32_e32 v225, 16, v157
	v_lshlrev_b32_e32 v224, 16, v156
	v_and_b32_e32 v157, 0xffff0000, v157
	v_and_b32_e32 v156, 0xffff0000, v156
	v_pk_fma_f32 v[174:175], v[228:229], v[216:217], v[174:175]
	v_pk_fma_f32 v[152:153], v[168:169], v[160:161], v[152:153]
	v_addc_co_u32_e32 v5, vcc, 0, v3, vcc
	v_pk_mul_f32 v[174:175], v[174:175], v[224:225]
	v_pk_mul_f32 v[152:153], v[152:153], v[156:157]
	v_bfe_u32 v162, v151, 16, 1
	v_bfe_u32 v163, v150, 16, 1
	v_add_co_u32_e32 v8, vcc, 0x24603000, v2
	v_bfe_u32 v156, v153, 16, 1
	v_bfe_u32 v157, v152, 16, 1
	v_add3_u32 v150, v150, v163, s5
	v_add3_u32 v151, v151, v162, s5
	v_bfe_u32 v162, v174, 16, 1
	v_bfe_u32 v163, v175, 16, 1
	v_addc_co_u32_e32 v9, vcc, 0, v3, vcc
	v_add3_u32 v152, v152, v157, s5
	v_add3_u32 v153, v153, v156, s5
	v_bfe_u32 v156, v146, 16, 1
	v_bfe_u32 v157, v147, 16, 1
	v_add3_u32 v163, v175, v163, s5
	v_add3_u32 v162, v174, v162, s5
	v_add_co_u32_e32 v2, vcc, 0x22603000, v2
	v_add3_u32 v147, v147, v157, s5
	v_add3_u32 v146, v146, v156, s5
	v_lshrrev_b32_e32 v156, 16, v162
	v_lshrrev_b32_e32 v157, 16, v163
	v_addc_co_u32_e32 v3, vcc, 0, v3, vcc
	v_lshrrev_b32_e32 v146, 16, v146
	v_and_or_b32 v153, v153, s1, v157
	v_and_or_b32 v152, v152, s1, v156
	v_lshl_add_u64 v[156:157], s[10:11], 0, v[186:187]
	v_lshrrev_b32_e32 v147, 16, v147
	v_and_or_b32 v150, v150, s1, v146
	v_add_co_u32_e32 v146, vcc, s13, v156
	v_and_or_b32 v151, v151, s1, v147
	s_nop 0
	v_addc_co_u32_e32 v147, vcc, 0, v157, vcc
	global_load_dwordx4 v[14:17], v[6:7], off offset:3072 nt
	global_load_dwordx4 v[10:13], v[4:5], off offset:3072 nt
	s_nop 0
	global_load_dwordx4 v[6:9], v[8:9], off offset:3072 nt
	s_nop 0
	global_load_dwordx4 v[2:5], v[2:3], off offset:3072 nt
	v_lshlrev_b32_e32 v163, 16, v143
	global_store_dwordx4 v[146:147], v[150:153], off nt
	v_lshlrev_b32_e32 v162, 16, v142
	v_and_b32_e32 v143, 0xffff0000, v143
	v_pk_mul_f32 v[152:153], v[158:159], v[214:215]
	v_lshlrev_b32_e32 v151, 16, v139
	v_pk_fma_f32 v[152:153], v[154:155], v[218:219], v[152:153]
	v_lshlrev_b32_e32 v150, 16, v138
	v_pk_fma_f32 v[152:153], v[210:211], v[162:163], v[152:153]
	v_and_b32_e32 v142, 0xffff0000, v142
	v_pk_mul_f32 v[150:151], v[152:153], v[150:151]
	v_pk_mul_f32 v[152:153], v[180:181], v[212:213]
	v_pk_mul_f32 v[170:171], v[226:227], v[216:217]
	v_pk_fma_f32 v[152:153], v[176:177], v[220:221], v[152:153]
	v_and_b32_e32 v139, 0xffff0000, v139
	v_and_b32_e32 v138, 0xffff0000, v138
	v_pk_fma_f32 v[152:153], v[184:185], v[142:143], v[152:153]
	v_lshlrev_b32_e32 v167, 16, v145
	v_lshlrev_b32_e32 v166, 16, v144
	v_pk_fma_f32 v[170:171], v[148:149], v[178:179], v[170:171]
	v_pk_mul_f32 v[138:139], v[152:153], v[138:139]
	v_lshlrev_b32_e32 v153, 16, v141
	v_lshlrev_b32_e32 v152, 16, v140
	v_pk_fma_f32 v[170:171], v[228:229], v[166:167], v[170:171]
	v_and_b32_e32 v145, 0xffff0000, v145
	v_pk_mul_f32 v[152:153], v[170:171], v[152:153]
	v_pk_mul_f32 v[170:171], v[172:173], v[160:161]
	v_and_b32_e32 v144, 0xffff0000, v144
	v_pk_fma_f32 v[170:171], v[164:165], v[182:183], v[170:171]
	v_and_b32_e32 v141, 0xffff0000, v141
	v_and_b32_e32 v140, 0xffff0000, v140
	v_pk_fma_f32 v[170:171], v[168:169], v[144:145], v[170:171]
	v_bfe_u32 v174, v139, 16, 1
	v_pk_mul_f32 v[140:141], v[170:171], v[140:141]
	v_bfe_u32 v175, v138, 16, 1
	v_bfe_u32 v170, v141, 16, 1
	v_bfe_u32 v171, v140, 16, 1
	v_add3_u32 v141, v141, v170, s5
	v_bfe_u32 v170, v150, 16, 1
	v_add3_u32 v138, v138, v175, s5
	v_add3_u32 v139, v139, v174, s5
	v_add3_u32 v140, v140, v171, s5
	v_bfe_u32 v171, v151, 16, 1
	v_bfe_u32 v174, v152, 16, 1
	v_bfe_u32 v175, v153, 16, 1
	v_add3_u32 v150, v150, v170, s5
	v_add3_u32 v153, v153, v175, s5
	v_add3_u32 v152, v152, v174, s5
	v_add3_u32 v151, v151, v171, s5
	v_lshrrev_b32_e32 v150, 16, v150
	v_lshrrev_b32_e32 v151, 16, v151
	v_lshrrev_b32_e32 v152, 16, v152
	v_lshrrev_b32_e32 v153, 16, v153
	v_and_or_b32 v138, v138, s1, v150
	v_add_co_u32_e32 v150, vcc, s15, v156
	v_and_or_b32 v141, v141, s1, v153
	v_and_or_b32 v140, v140, s1, v152
	v_and_or_b32 v139, v139, s1, v151
	v_addc_co_u32_e32 v151, vcc, 0, v157, vcc
	v_pk_mul_f32 v[152:153], v[158:159], v[162:163]
	global_store_dwordx4 v[150:151], v[138:141], off nt
	v_pk_fma_f32 v[152:153], v[154:155], v[214:215], v[152:153]
	v_pk_mul_f32 v[174:175], v[226:227], v[166:167]
	v_lshlrev_b32_e32 v139, 16, v135
	v_lshlrev_b32_e32 v138, 16, v134
	v_lshlrev_b32_e32 v141, 16, v131
	v_lshlrev_b32_e32 v140, 16, v130
	v_pk_fma_f32 v[152:153], v[210:211], v[138:139], v[152:153]
	v_and_b32_e32 v135, 0xffff0000, v135
	v_pk_mul_f32 v[140:141], v[152:153], v[140:141]
	v_pk_mul_f32 v[152:153], v[180:181], v[142:143]
	v_and_b32_e32 v134, 0xffff0000, v134
	v_pk_fma_f32 v[152:153], v[176:177], v[212:213], v[152:153]
	v_and_b32_e32 v131, 0xffff0000, v131
	v_and_b32_e32 v130, 0xffff0000, v130
	v_pk_fma_f32 v[152:153], v[184:185], v[134:135], v[152:153]
	v_lshlrev_b32_e32 v171, 16, v137
	v_lshlrev_b32_e32 v170, 16, v136
	v_pk_fma_f32 v[174:175], v[148:149], v[216:217], v[174:175]
	v_pk_mul_f32 v[130:131], v[152:153], v[130:131]
	v_lshlrev_b32_e32 v153, 16, v133
	v_lshlrev_b32_e32 v152, 16, v132
	v_pk_fma_f32 v[174:175], v[228:229], v[170:171], v[174:175]
	v_and_b32_e32 v137, 0xffff0000, v137
	v_pk_mul_f32 v[152:153], v[174:175], v[152:153]
	v_pk_mul_f32 v[174:175], v[172:173], v[144:145]
	v_and_b32_e32 v136, 0xffff0000, v136
	v_pk_fma_f32 v[160:161], v[164:165], v[160:161], v[174:175]
	v_and_b32_e32 v133, 0xffff0000, v133
	v_and_b32_e32 v132, 0xffff0000, v132
	v_pk_fma_f32 v[160:161], v[168:169], v[136:137], v[160:161]
	v_bfe_u32 v174, v131, 16, 1
	v_pk_mul_f32 v[132:133], v[160:161], v[132:133]
	v_bfe_u32 v175, v130, 16, 1
	v_bfe_u32 v160, v133, 16, 1
	v_bfe_u32 v161, v132, 16, 1
	v_add3_u32 v131, v131, v174, s5
	v_bfe_u32 v174, v152, 16, 1
	v_add3_u32 v130, v130, v175, s5
	v_add3_u32 v132, v132, v161, s5
	v_add3_u32 v133, v133, v160, s5
	v_bfe_u32 v160, v140, 16, 1
	v_bfe_u32 v161, v141, 16, 1
	v_bfe_u32 v175, v153, 16, 1
	v_add3_u32 v152, v152, v174, s5
	v_add3_u32 v153, v153, v175, s5
	v_add3_u32 v141, v141, v161, s5
	v_add3_u32 v140, v140, v160, s5
	v_lshrrev_b32_e32 v152, 16, v152
	v_lshrrev_b32_e32 v140, 16, v140
	v_lshrrev_b32_e32 v141, 16, v141
	v_lshrrev_b32_e32 v153, 16, v153
	v_and_or_b32 v132, v132, s1, v152
	v_add_co_u32_e32 v152, vcc, s30, v156
	v_and_or_b32 v133, v133, s1, v153
	v_and_or_b32 v131, v131, s1, v141
	v_and_or_b32 v130, v130, s1, v140
	v_addc_co_u32_e32 v153, vcc, 0, v157, vcc
	v_pk_mul_f32 v[138:139], v[158:159], v[138:139]
	global_store_dwordx4 v[152:153], v[130:133], off nt
	v_pk_fma_f32 v[138:139], v[154:155], v[162:163], v[138:139]
	v_lshlrev_b32_e32 v155, 16, v111
	v_lshlrev_b32_e32 v131, 16, v127
	v_lshlrev_b32_e32 v130, 16, v126
	v_lshlrev_b32_e32 v133, 16, v123
	v_lshlrev_b32_e32 v132, 16, v122
	v_pk_fma_f32 v[130:131], v[210:211], v[130:131], v[138:139]
	v_and_b32_e32 v127, 0xffff0000, v127
	v_pk_mul_f32 v[130:131], v[130:131], v[132:133]
	v_pk_mul_f32 v[132:133], v[180:181], v[134:135]
	v_and_b32_e32 v126, 0xffff0000, v126
	v_pk_fma_f32 v[132:133], v[176:177], v[142:143], v[132:133]
	v_and_b32_e32 v123, 0xffff0000, v123
	v_and_b32_e32 v122, 0xffff0000, v122
	v_pk_fma_f32 v[126:127], v[184:185], v[126:127], v[132:133]
	v_pk_mul_f32 v[134:135], v[226:227], v[170:171]
	v_pk_mul_f32 v[122:123], v[126:127], v[122:123]
	v_lshlrev_b32_e32 v127, 16, v129
	v_lshlrev_b32_e32 v126, 16, v128
	v_pk_fma_f32 v[134:135], v[148:149], v[166:167], v[134:135]
	v_lshlrev_b32_e32 v133, 16, v125
	v_lshlrev_b32_e32 v132, 16, v124
	v_pk_fma_f32 v[126:127], v[228:229], v[126:127], v[134:135]
	v_and_b32_e32 v129, 0xffff0000, v129
	v_pk_mul_f32 v[126:127], v[126:127], v[132:133]
	v_pk_mul_f32 v[132:133], v[172:173], v[136:137]
	v_and_b32_e32 v128, 0xffff0000, v128
	v_pk_fma_f32 v[132:133], v[164:165], v[144:145], v[132:133]
	v_and_b32_e32 v125, 0xffff0000, v125
	v_and_b32_e32 v124, 0xffff0000, v124
	v_pk_fma_f32 v[128:129], v[168:169], v[128:129], v[132:133]
	v_bfe_u32 v132, v123, 16, 1
	v_pk_mul_f32 v[124:125], v[128:129], v[124:125]
	v_bfe_u32 v133, v122, 16, 1
	v_bfe_u32 v128, v125, 16, 1
	v_bfe_u32 v129, v124, 16, 1
	v_add3_u32 v122, v122, v133, s5
	v_add3_u32 v123, v123, v132, s5
	v_add3_u32 v124, v124, v129, s5
	v_add3_u32 v125, v125, v128, s5
	v_bfe_u32 v128, v130, 16, 1
	v_bfe_u32 v129, v131, 16, 1
	v_bfe_u32 v132, v126, 16, 1
	v_bfe_u32 v133, v127, 16, 1
	v_add3_u32 v127, v127, v133, s5
	v_add3_u32 v126, v126, v132, s5
	v_add3_u32 v129, v131, v129, s5
	v_add3_u32 v128, v130, v128, s5
	v_lshrrev_b32_e32 v128, 16, v128
	v_lshrrev_b32_e32 v129, 16, v129
	v_lshrrev_b32_e32 v126, 16, v126
	v_lshrrev_b32_e32 v127, 16, v127
	v_add_co_u32_e32 v148, vcc, s31, v156
	v_and_or_b32 v125, v125, s1, v127
	v_and_or_b32 v124, v124, s1, v126
	v_and_or_b32 v123, v123, s1, v129
	v_and_or_b32 v122, v122, s1, v128
	v_addc_co_u32_e32 v149, vcc, 0, v157, vcc
	global_store_dwordx4 v[148:149], v[122:125], off nt
	global_load_dwordx4 v[134:137], v[188:189], off offset:2048
	global_load_dwordx4 v[138:141], v[194:195], off
	global_load_dwordx4 v[142:145], v[196:197], off
	s_nop 0
	global_load_dwordx4 v[122:125], v[188:189], off offset:2064
	global_load_dwordx4 v[130:133], v[194:195], off offset:16
	global_load_dwordx4 v[126:129], v[196:197], off offset:16
	v_lshlrev_b32_e32 v154, 16, v110
	v_and_b32_e32 v157, 0xffff0000, v111
	v_and_b32_e32 v156, 0xffff0000, v110
	v_lshlrev_b32_e32 v159, 16, v107
	v_lshlrev_b32_e32 v158, 16, v106
	v_and_b32_e32 v161, 0xffff0000, v107
	v_and_b32_e32 v160, 0xffff0000, v106
	v_lshlrev_b32_e32 v163, 16, v119
	v_lshlrev_b32_e32 v162, 16, v118
	v_and_b32_e32 v165, 0xffff0000, v119
	v_and_b32_e32 v164, 0xffff0000, v118
	v_lshlrev_b32_e32 v119, 16, v115
	v_lshlrev_b32_e32 v118, 16, v114
	v_and_b32_e32 v167, 0xffff0000, v115
	v_and_b32_e32 v166, 0xffff0000, v114
	s_add_u32 s10, s10, s16
	s_addc_u32 s11, s11, s17
	s_add_u32 s18, s18, s20
	s_addc_u32 s19, s19, s21
	s_cmpk_lt_i32 s0, 0x2000
	s_waitcnt vmcnt(5)
	v_mov_b32_e32 v106, v134
	s_waitcnt vmcnt(4)
	v_mov_b32_e32 v110, v138
	v_mov_b32_e32 v111, v140
	v_mov_b32_e32 v140, v139
	v_mov_b32_e32 v107, v136
	v_pk_mul_f32 v[114:115], v[110:111], v[158:159]
	v_mov_b32_e32 v136, v135
	v_pk_mul_f32 v[134:135], v[140:141], v[160:161]
	v_pk_fma_f32 v[154:155], v[106:107], v[154:155], v[114:115]
	s_waitcnt vmcnt(3)
	v_mov_b32_e32 v115, v144
	v_pk_fma_f32 v[134:135], v[136:137], v[156:157], v[134:135]
	v_mov_b32_e32 v144, v143
	v_mov_b32_e32 v114, v142
	v_pk_fma_f32 v[134:135], v[144:145], v[164:165], v[134:135]
	v_lshlrev_b32_e32 v143, 16, v109
	v_lshlrev_b32_e32 v142, 16, v108
	v_and_b32_e32 v109, 0xffff0000, v109
	v_and_b32_e32 v108, 0xffff0000, v108
	s_waitcnt vmcnt(1)
	v_mov_b32_e32 v168, v130
	v_mov_b32_e32 v169, v132
	v_mov_b32_e32 v132, v131
	v_pk_fma_f32 v[154:155], v[114:115], v[162:163], v[154:155]
	v_pk_mul_f32 v[134:135], v[134:135], v[166:167]
	v_lshlrev_b32_e32 v139, 16, v113
	v_lshlrev_b32_e32 v138, 16, v112
	v_and_b32_e32 v113, 0xffff0000, v113
	v_and_b32_e32 v112, 0xffff0000, v112
	v_mov_b32_e32 v166, v122
	v_mov_b32_e32 v167, v124
	v_pk_mul_f32 v[170:171], v[168:169], v[142:143]
	v_mov_b32_e32 v124, v123
	v_pk_mul_f32 v[122:123], v[132:133], v[108:109]
	v_pk_mul_f32 v[118:119], v[154:155], v[118:119]
	v_lshlrev_b32_e32 v155, 16, v121
	v_lshlrev_b32_e32 v154, 16, v120
	v_and_b32_e32 v121, 0xffff0000, v121
	v_and_b32_e32 v120, 0xffff0000, v120
	v_pk_fma_f32 v[138:139], v[166:167], v[138:139], v[170:171]
	s_waitcnt vmcnt(0)
	v_mov_b32_e32 v171, v128
	v_pk_fma_f32 v[112:113], v[124:125], v[112:113], v[122:123]
	v_mov_b32_e32 v128, v127
	v_lshlrev_b32_e32 v157, 16, v117
	v_lshlrev_b32_e32 v156, 16, v116
	v_and_b32_e32 v117, 0xffff0000, v117
	v_and_b32_e32 v116, 0xffff0000, v116
	v_mov_b32_e32 v170, v126
	v_pk_fma_f32 v[112:113], v[128:129], v[120:121], v[112:113]
	v_pk_fma_f32 v[138:139], v[170:171], v[154:155], v[138:139]
	v_pk_mul_f32 v[112:113], v[112:113], v[116:117]
	v_pk_mul_f32 v[138:139], v[138:139], v[156:157]
	v_bfe_u32 v116, v113, 16, 1
	v_bfe_u32 v117, v112, 16, 1
	v_add3_u32 v112, v112, v117, s5
	v_add3_u32 v113, v113, v116, s5
	v_bfe_u32 v116, v118, 16, 1
	v_bfe_u32 v117, v119, 16, 1
	v_bfe_u32 v126, v138, 16, 1
	v_bfe_u32 v127, v139, 16, 1
	v_bfe_u32 v122, v135, 16, 1
	v_bfe_u32 v123, v134, 16, 1
	v_add3_u32 v127, v139, v127, s5
	v_add3_u32 v126, v138, v126, s5
	v_add3_u32 v117, v119, v117, s5
	v_add3_u32 v116, v118, v116, s5
	v_add3_u32 v123, v134, v123, s5
	v_add3_u32 v122, v135, v122, s5
	v_lshrrev_b32_e32 v116, 16, v116
	v_lshrrev_b32_e32 v117, 16, v117
	v_lshrrev_b32_e32 v118, 16, v126
	v_lshrrev_b32_e32 v119, 16, v127
	v_and_or_b32 v119, v113, s1, v119
	v_and_or_b32 v118, v112, s1, v118
	v_and_or_b32 v117, v122, s1, v117
	v_and_or_b32 v116, v123, s1, v116
	global_store_dwordx4 v[146:147], v[116:119], off offset:1024 nt
	v_lshlrev_b32_e32 v113, 16, v103
	v_lshlrev_b32_e32 v112, 16, v102
	v_pk_mul_f32 v[118:119], v[110:111], v[162:163]
	v_lshlrev_b32_e32 v117, 16, v99
	v_pk_fma_f32 v[118:119], v[106:107], v[158:159], v[118:119]
	v_lshlrev_b32_e32 v116, 16, v98
	v_pk_fma_f32 v[118:119], v[114:115], v[112:113], v[118:119]
	v_and_b32_e32 v103, 0xffff0000, v103
	v_pk_mul_f32 v[116:117], v[118:119], v[116:117]
	v_pk_mul_f32 v[118:119], v[140:141], v[164:165]
	v_and_b32_e32 v102, 0xffff0000, v102
	v_pk_fma_f32 v[118:119], v[136:137], v[160:161], v[118:119]
	v_and_b32_e32 v99, 0xffff0000, v99
	v_and_b32_e32 v98, 0xffff0000, v98
	v_pk_fma_f32 v[118:119], v[144:145], v[102:103], v[118:119]
	v_pk_mul_f32 v[126:127], v[168:169], v[154:155]
	v_pk_mul_f32 v[98:99], v[118:119], v[98:99]
	v_lshlrev_b32_e32 v119, 16, v105
	v_lshlrev_b32_e32 v118, 16, v104
	v_pk_fma_f32 v[126:127], v[166:167], v[142:143], v[126:127]
	v_lshlrev_b32_e32 v123, 16, v101
	v_lshlrev_b32_e32 v122, 16, v100
	v_pk_fma_f32 v[126:127], v[170:171], v[118:119], v[126:127]
	v_and_b32_e32 v105, 0xffff0000, v105
	v_pk_mul_f32 v[122:123], v[126:127], v[122:123]
	v_pk_mul_f32 v[126:127], v[132:133], v[120:121]
	v_and_b32_e32 v104, 0xffff0000, v104
	v_pk_fma_f32 v[108:109], v[124:125], v[108:109], v[126:127]
	v_and_b32_e32 v101, 0xffff0000, v101
	v_and_b32_e32 v100, 0xffff0000, v100
	v_pk_fma_f32 v[108:109], v[128:129], v[104:105], v[108:109]
	v_bfe_u32 v126, v99, 16, 1
	v_pk_mul_f32 v[100:101], v[108:109], v[100:101]
	v_bfe_u32 v127, v98, 16, 1
	v_bfe_u32 v108, v101, 16, 1
	v_bfe_u32 v109, v100, 16, 1
	v_add3_u32 v98, v98, v127, s5
	v_add3_u32 v99, v99, v126, s5
	v_add3_u32 v100, v100, v109, s5
	v_add3_u32 v101, v101, v108, s5
	v_bfe_u32 v108, v116, 16, 1
	v_bfe_u32 v109, v117, 16, 1
	v_bfe_u32 v126, v122, 16, 1
	v_bfe_u32 v127, v123, 16, 1
	v_add3_u32 v123, v123, v127, s5
	v_add3_u32 v122, v122, v126, s5
	v_add3_u32 v109, v117, v109, s5
	v_add3_u32 v108, v116, v108, s5
	v_lshrrev_b32_e32 v108, 16, v108
	v_lshrrev_b32_e32 v109, 16, v109
	v_lshrrev_b32_e32 v116, 16, v122
	v_lshrrev_b32_e32 v117, 16, v123
	v_and_or_b32 v101, v101, s1, v117
	v_and_or_b32 v100, v100, s1, v116
	v_and_or_b32 v99, v99, s1, v109
	v_and_or_b32 v98, v98, s1, v108
	v_pk_mul_f32 v[108:109], v[110:111], v[112:113]
	global_store_dwordx4 v[150:151], v[98:101], off offset:1024 nt
	v_pk_fma_f32 v[108:109], v[106:107], v[162:163], v[108:109]
	v_pk_mul_f32 v[122:123], v[168:169], v[118:119]
	v_lshlrev_b32_e32 v99, 16, v95
	v_lshlrev_b32_e32 v98, 16, v94
	v_lshlrev_b32_e32 v101, 16, v91
	v_lshlrev_b32_e32 v100, 16, v90
	v_pk_fma_f32 v[108:109], v[114:115], v[98:99], v[108:109]
	v_and_b32_e32 v95, 0xffff0000, v95
	v_pk_mul_f32 v[100:101], v[108:109], v[100:101]
	v_pk_mul_f32 v[108:109], v[140:141], v[102:103]
	v_and_b32_e32 v94, 0xffff0000, v94
	v_pk_fma_f32 v[108:109], v[136:137], v[164:165], v[108:109]
	v_and_b32_e32 v91, 0xffff0000, v91
	v_and_b32_e32 v90, 0xffff0000, v90
	v_pk_fma_f32 v[108:109], v[144:145], v[94:95], v[108:109]
	v_pk_fma_f32 v[122:123], v[166:167], v[154:155], v[122:123]
	v_pk_mul_f32 v[90:91], v[108:109], v[90:91]
	v_lshlrev_b32_e32 v109, 16, v97
	v_lshlrev_b32_e32 v108, 16, v96
	v_lshlrev_b32_e32 v117, 16, v93
	v_lshlrev_b32_e32 v116, 16, v92
	v_pk_fma_f32 v[122:123], v[170:171], v[108:109], v[122:123]
	v_and_b32_e32 v97, 0xffff0000, v97
	v_pk_mul_f32 v[116:117], v[122:123], v[116:117]
	v_pk_mul_f32 v[122:123], v[132:133], v[104:105]
	v_and_b32_e32 v96, 0xffff0000, v96
	v_pk_fma_f32 v[120:121], v[124:125], v[120:121], v[122:123]
	v_and_b32_e32 v93, 0xffff0000, v93
	v_and_b32_e32 v92, 0xffff0000, v92
	v_pk_fma_f32 v[120:121], v[128:129], v[96:97], v[120:121]
	v_bfe_u32 v122, v91, 16, 1
	v_pk_mul_f32 v[92:93], v[120:121], v[92:93]
	v_bfe_u32 v123, v90, 16, 1
	v_bfe_u32 v120, v93, 16, 1
	v_bfe_u32 v121, v92, 16, 1
	v_add3_u32 v90, v90, v123, s5
	v_add3_u32 v91, v91, v122, s5
	v_add3_u32 v92, v92, v121, s5
	v_add3_u32 v93, v93, v120, s5
	v_bfe_u32 v120, v100, 16, 1
	v_bfe_u32 v121, v101, 16, 1
	v_bfe_u32 v122, v116, 16, 1
	v_bfe_u32 v123, v117, 16, 1
	v_add3_u32 v117, v117, v123, s5
	v_add3_u32 v116, v116, v122, s5
	v_add3_u32 v101, v101, v121, s5
	v_add3_u32 v100, v100, v120, s5
	v_lshrrev_b32_e32 v100, 16, v100
	v_lshrrev_b32_e32 v101, 16, v101
	v_lshrrev_b32_e32 v116, 16, v116
	v_lshrrev_b32_e32 v117, 16, v117
	v_and_or_b32 v93, v93, s1, v117
	v_and_or_b32 v92, v92, s1, v116
	v_and_or_b32 v91, v91, s1, v101
	v_and_or_b32 v90, v90, s1, v100
	v_pk_mul_f32 v[98:99], v[110:111], v[98:99]
	global_store_dwordx4 v[152:153], v[90:93], off offset:1024 nt
	v_pk_fma_f32 v[98:99], v[106:107], v[112:113], v[98:99]
	v_lshlrev_b32_e32 v107, 16, v71
	v_lshlrev_b32_e32 v91, 16, v87
	v_lshlrev_b32_e32 v90, 16, v86
	v_lshlrev_b32_e32 v93, 16, v83
	v_lshlrev_b32_e32 v92, 16, v82
	v_pk_fma_f32 v[90:91], v[114:115], v[90:91], v[98:99]
	v_and_b32_e32 v87, 0xffff0000, v87
	v_pk_mul_f32 v[90:91], v[90:91], v[92:93]
	v_pk_mul_f32 v[92:93], v[140:141], v[94:95]
	v_and_b32_e32 v86, 0xffff0000, v86
	v_pk_fma_f32 v[92:93], v[136:137], v[102:103], v[92:93]
	v_and_b32_e32 v83, 0xffff0000, v83
	v_and_b32_e32 v82, 0xffff0000, v82
	v_pk_fma_f32 v[86:87], v[144:145], v[86:87], v[92:93]
	v_pk_mul_f32 v[94:95], v[168:169], v[108:109]
	v_pk_mul_f32 v[82:83], v[86:87], v[82:83]
	v_lshlrev_b32_e32 v87, 16, v89
	v_lshlrev_b32_e32 v86, 16, v88
	v_pk_fma_f32 v[94:95], v[166:167], v[118:119], v[94:95]
	v_lshlrev_b32_e32 v93, 16, v85
	v_lshlrev_b32_e32 v92, 16, v84
	v_pk_fma_f32 v[86:87], v[170:171], v[86:87], v[94:95]
	v_and_b32_e32 v89, 0xffff0000, v89
	v_pk_mul_f32 v[86:87], v[86:87], v[92:93]
	v_pk_mul_f32 v[92:93], v[132:133], v[96:97]
	v_and_b32_e32 v88, 0xffff0000, v88
	v_pk_fma_f32 v[92:93], v[124:125], v[104:105], v[92:93]
	v_and_b32_e32 v85, 0xffff0000, v85
	v_and_b32_e32 v84, 0xffff0000, v84
	v_pk_fma_f32 v[88:89], v[128:129], v[88:89], v[92:93]
	v_bfe_u32 v92, v83, 16, 1
	v_pk_mul_f32 v[84:85], v[88:89], v[84:85]
	v_bfe_u32 v93, v82, 16, 1
	v_bfe_u32 v88, v85, 16, 1
	v_bfe_u32 v89, v84, 16, 1
	v_add3_u32 v82, v82, v93, s5
	v_add3_u32 v83, v83, v92, s5
	v_add3_u32 v84, v84, v89, s5
	v_add3_u32 v85, v85, v88, s5
	v_bfe_u32 v88, v90, 16, 1
	v_bfe_u32 v89, v91, 16, 1
	v_bfe_u32 v92, v86, 16, 1
	v_bfe_u32 v93, v87, 16, 1
	v_add3_u32 v87, v87, v93, s5
	v_add3_u32 v86, v86, v92, s5
	v_add3_u32 v89, v91, v89, s5
	v_add3_u32 v88, v90, v88, s5
	v_lshrrev_b32_e32 v88, 16, v88
	v_lshrrev_b32_e32 v89, 16, v89
	v_lshrrev_b32_e32 v86, 16, v86
	v_lshrrev_b32_e32 v87, 16, v87
	v_and_or_b32 v85, v85, s1, v87
	v_and_or_b32 v84, v84, s1, v86
	v_and_or_b32 v83, v83, s1, v89
	v_and_or_b32 v82, v82, s1, v88
	global_store_dwordx4 v[148:149], v[82:85], off offset:1024 nt
	global_load_dwordx4 v[94:97], v[198:199], off
	global_load_dwordx4 v[98:101], v[200:201], off
	global_load_dwordx4 v[102:105], v[202:203], off
	s_nop 0
	global_load_dwordx4 v[82:85], v[198:199], off offset:16
	global_load_dwordx4 v[90:93], v[200:201], off offset:16
	global_load_dwordx4 v[86:89], v[202:203], off offset:16
	v_lshlrev_b32_e32 v106, 16, v70
	v_and_b32_e32 v109, 0xffff0000, v71
	v_and_b32_e32 v108, 0xffff0000, v70
	v_lshlrev_b32_e32 v111, 16, v51
	v_lshlrev_b32_e32 v110, 16, v50
	v_and_b32_e32 v113, 0xffff0000, v51
	v_and_b32_e32 v112, 0xffff0000, v50
	v_lshlrev_b32_e32 v115, 16, v79
	v_lshlrev_b32_e32 v114, 16, v78
	v_and_b32_e32 v117, 0xffff0000, v79
	v_and_b32_e32 v116, 0xffff0000, v78
	v_lshlrev_b32_e32 v79, 16, v75
	v_lshlrev_b32_e32 v78, 16, v74
	v_and_b32_e32 v119, 0xffff0000, v75
	v_and_b32_e32 v118, 0xffff0000, v74
	s_waitcnt vmcnt(5)
	v_mov_b32_e32 v50, v94
	s_waitcnt vmcnt(4)
	v_mov_b32_e32 v70, v98
	v_mov_b32_e32 v71, v100
	v_mov_b32_e32 v100, v99
	v_mov_b32_e32 v51, v96
	v_pk_mul_f32 v[74:75], v[70:71], v[110:111]
	v_mov_b32_e32 v96, v95
	v_pk_mul_f32 v[94:95], v[100:101], v[112:113]
	v_pk_fma_f32 v[106:107], v[50:51], v[106:107], v[74:75]
	s_waitcnt vmcnt(3)
	v_mov_b32_e32 v75, v104
	v_pk_fma_f32 v[94:95], v[96:97], v[108:109], v[94:95]
	v_mov_b32_e32 v104, v103
	v_mov_b32_e32 v74, v102
	v_pk_fma_f32 v[94:95], v[104:105], v[116:117], v[94:95]
	v_lshlrev_b32_e32 v103, 16, v53
	v_lshlrev_b32_e32 v102, 16, v52
	v_and_b32_e32 v53, 0xffff0000, v53
	v_and_b32_e32 v52, 0xffff0000, v52
	s_waitcnt vmcnt(1)
	v_mov_b32_e32 v120, v90
	v_mov_b32_e32 v121, v92
	v_mov_b32_e32 v92, v91
	v_pk_fma_f32 v[106:107], v[74:75], v[114:115], v[106:107]
	v_pk_mul_f32 v[94:95], v[94:95], v[118:119]
	v_lshlrev_b32_e32 v99, 16, v73
	v_lshlrev_b32_e32 v98, 16, v72
	v_and_b32_e32 v73, 0xffff0000, v73
	v_and_b32_e32 v72, 0xffff0000, v72
	v_mov_b32_e32 v118, v82
	v_mov_b32_e32 v119, v84
	v_pk_mul_f32 v[122:123], v[120:121], v[102:103]
	v_mov_b32_e32 v84, v83
	v_pk_mul_f32 v[82:83], v[92:93], v[52:53]
	v_pk_mul_f32 v[78:79], v[106:107], v[78:79]
	v_lshlrev_b32_e32 v107, 16, v81
	v_lshlrev_b32_e32 v106, 16, v80
	v_and_b32_e32 v81, 0xffff0000, v81
	v_and_b32_e32 v80, 0xffff0000, v80
	v_pk_fma_f32 v[98:99], v[118:119], v[98:99], v[122:123]
	s_waitcnt vmcnt(0)
	v_mov_b32_e32 v123, v88
	v_pk_fma_f32 v[72:73], v[84:85], v[72:73], v[82:83]
	v_mov_b32_e32 v88, v87
	v_lshlrev_b32_e32 v109, 16, v77
	v_lshlrev_b32_e32 v108, 16, v76
	v_and_b32_e32 v77, 0xffff0000, v77
	v_and_b32_e32 v76, 0xffff0000, v76
	v_mov_b32_e32 v122, v86
	v_pk_fma_f32 v[72:73], v[88:89], v[80:81], v[72:73]
	v_pk_fma_f32 v[98:99], v[122:123], v[106:107], v[98:99]
	v_pk_mul_f32 v[72:73], v[72:73], v[76:77]
	v_pk_mul_f32 v[98:99], v[98:99], v[108:109]
	v_bfe_u32 v76, v73, 16, 1
	v_bfe_u32 v77, v72, 16, 1
	v_add3_u32 v72, v72, v77, s5
	v_add3_u32 v73, v73, v76, s5
	v_bfe_u32 v76, v78, 16, 1
	v_bfe_u32 v77, v79, 16, 1
	v_bfe_u32 v86, v98, 16, 1
	v_bfe_u32 v87, v99, 16, 1
	v_bfe_u32 v82, v95, 16, 1
	v_bfe_u32 v83, v94, 16, 1
	v_add3_u32 v87, v99, v87, s5
	v_add3_u32 v86, v98, v86, s5
	v_add3_u32 v77, v79, v77, s5
	v_add3_u32 v76, v78, v76, s5
	v_add3_u32 v83, v94, v83, s5
	v_add3_u32 v82, v95, v82, s5
	v_lshrrev_b32_e32 v76, 16, v76
	v_lshrrev_b32_e32 v77, 16, v77
	v_lshrrev_b32_e32 v78, 16, v86
	v_lshrrev_b32_e32 v79, 16, v87
	v_and_or_b32 v79, v73, s1, v79
	v_and_or_b32 v78, v72, s1, v78
	v_and_or_b32 v77, v82, s1, v77
	v_and_or_b32 v76, v83, s1, v76
	global_store_dwordx4 v[146:147], v[76:79], off offset:2048 nt
	v_lshlrev_b32_e32 v73, 16, v67
	v_lshlrev_b32_e32 v72, 16, v66
	v_pk_mul_f32 v[78:79], v[70:71], v[114:115]
	v_lshlrev_b32_e32 v77, 16, v63
	v_pk_fma_f32 v[78:79], v[50:51], v[110:111], v[78:79]
	v_lshlrev_b32_e32 v76, 16, v62
	v_pk_fma_f32 v[78:79], v[74:75], v[72:73], v[78:79]
	v_and_b32_e32 v67, 0xffff0000, v67
	v_pk_mul_f32 v[76:77], v[78:79], v[76:77]
	v_pk_mul_f32 v[78:79], v[100:101], v[116:117]
	v_and_b32_e32 v66, 0xffff0000, v66
	v_pk_fma_f32 v[78:79], v[96:97], v[112:113], v[78:79]
	v_and_b32_e32 v63, 0xffff0000, v63
	v_and_b32_e32 v62, 0xffff0000, v62
	v_pk_fma_f32 v[78:79], v[104:105], v[66:67], v[78:79]
	v_pk_mul_f32 v[86:87], v[120:121], v[106:107]
	v_pk_mul_f32 v[62:63], v[78:79], v[62:63]
	v_lshlrev_b32_e32 v79, 16, v69
	v_lshlrev_b32_e32 v78, 16, v68
	v_pk_fma_f32 v[86:87], v[118:119], v[102:103], v[86:87]
	v_lshlrev_b32_e32 v83, 16, v65
	v_lshlrev_b32_e32 v82, 16, v64
	v_pk_fma_f32 v[86:87], v[122:123], v[78:79], v[86:87]
	v_and_b32_e32 v69, 0xffff0000, v69
	v_pk_mul_f32 v[82:83], v[86:87], v[82:83]
	v_pk_mul_f32 v[86:87], v[92:93], v[80:81]
	v_and_b32_e32 v68, 0xffff0000, v68
	v_pk_fma_f32 v[52:53], v[84:85], v[52:53], v[86:87]
	v_and_b32_e32 v65, 0xffff0000, v65
	v_and_b32_e32 v64, 0xffff0000, v64
	v_pk_fma_f32 v[52:53], v[88:89], v[68:69], v[52:53]
	v_bfe_u32 v86, v63, 16, 1
	v_pk_mul_f32 v[52:53], v[52:53], v[64:65]
	v_bfe_u32 v87, v62, 16, 1
	v_bfe_u32 v64, v53, 16, 1
	v_bfe_u32 v65, v52, 16, 1
	v_add3_u32 v62, v62, v87, s5
	v_add3_u32 v63, v63, v86, s5
	v_add3_u32 v52, v52, v65, s5
	v_add3_u32 v53, v53, v64, s5
	v_bfe_u32 v64, v76, 16, 1
	v_bfe_u32 v65, v77, 16, 1
	v_bfe_u32 v86, v82, 16, 1
	v_bfe_u32 v87, v83, 16, 1
	v_add3_u32 v83, v83, v87, s5
	v_add3_u32 v82, v82, v86, s5
	v_add3_u32 v65, v77, v65, s5
	v_add3_u32 v64, v76, v64, s5
	v_lshrrev_b32_e32 v76, 16, v64
	v_lshrrev_b32_e32 v77, 16, v65
	v_lshrrev_b32_e32 v64, 16, v82
	v_lshrrev_b32_e32 v65, 16, v83
	v_and_or_b32 v65, v53, s1, v65
	v_and_or_b32 v64, v52, s1, v64
	v_and_or_b32 v63, v63, s1, v77
	v_and_or_b32 v62, v62, s1, v76
	global_store_dwordx4 v[150:151], v[62:65], off offset:2048 nt
	v_lshlrev_b32_e32 v53, 16, v55
	v_lshlrev_b32_e32 v52, 16, v54
	v_pk_mul_f32 v[64:65], v[70:71], v[72:73]
	v_lshlrev_b32_e32 v63, 16, v59
	v_lshlrev_b32_e32 v62, 16, v58
	v_pk_fma_f32 v[64:65], v[50:51], v[114:115], v[64:65]
	v_and_b32_e32 v59, 0xffff0000, v59
	v_pk_fma_f32 v[64:65], v[74:75], v[62:63], v[64:65]
	v_and_b32_e32 v58, 0xffff0000, v58
	v_pk_mul_f32 v[52:53], v[64:65], v[52:53]
	v_pk_mul_f32 v[64:65], v[100:101], v[66:67]
	v_and_b32_e32 v55, 0xffff0000, v55
	v_pk_fma_f32 v[64:65], v[96:97], v[116:117], v[64:65]
	v_and_b32_e32 v54, 0xffff0000, v54
	v_pk_fma_f32 v[64:65], v[104:105], v[58:59], v[64:65]
	v_pk_mul_f32 v[82:83], v[120:121], v[78:79]
	v_pk_mul_f32 v[54:55], v[64:65], v[54:55]
	v_lshlrev_b32_e32 v65, 16, v61
	v_lshlrev_b32_e32 v64, 16, v60
	v_pk_fma_f32 v[82:83], v[118:119], v[106:107], v[82:83]
	v_lshlrev_b32_e32 v77, 16, v57
	v_lshlrev_b32_e32 v76, 16, v56
	v_pk_fma_f32 v[82:83], v[122:123], v[64:65], v[82:83]
	v_and_b32_e32 v61, 0xffff0000, v61
	v_pk_mul_f32 v[76:77], v[82:83], v[76:77]
	v_pk_mul_f32 v[82:83], v[92:93], v[68:69]
	v_and_b32_e32 v60, 0xffff0000, v60
	v_pk_fma_f32 v[80:81], v[84:85], v[80:81], v[82:83]
	v_and_b32_e32 v57, 0xffff0000, v57
	v_and_b32_e32 v56, 0xffff0000, v56
	v_pk_fma_f32 v[80:81], v[88:89], v[60:61], v[80:81]
	v_bfe_u32 v82, v55, 16, 1
	v_pk_mul_f32 v[56:57], v[80:81], v[56:57]
	v_bfe_u32 v83, v54, 16, 1
	v_bfe_u32 v80, v57, 16, 1
	v_bfe_u32 v81, v56, 16, 1
	v_add3_u32 v83, v54, v83, s5
	v_add3_u32 v82, v55, v82, s5
	v_add3_u32 v54, v56, v81, s5
	v_add3_u32 v55, v57, v80, s5
	v_bfe_u32 v56, v52, 16, 1
	v_bfe_u32 v57, v53, 16, 1
	v_bfe_u32 v80, v76, 16, 1
	v_bfe_u32 v81, v77, 16, 1
	v_add3_u32 v77, v77, v81, s5
	v_add3_u32 v76, v76, v80, s5
	v_add3_u32 v53, v53, v57, s5
	v_add3_u32 v52, v52, v56, s5
	v_lshrrev_b32_e32 v52, 16, v52
	v_lshrrev_b32_e32 v53, 16, v53
	v_lshrrev_b32_e32 v56, 16, v76
	v_lshrrev_b32_e32 v57, 16, v77
	v_and_or_b32 v55, v55, s1, v57
	v_and_or_b32 v54, v54, s1, v56
	v_and_or_b32 v53, v82, s1, v53
	v_and_or_b32 v52, v83, s1, v52
	v_pk_mul_f32 v[56:57], v[70:71], v[62:63]
	global_store_dwordx4 v[152:153], v[52:55], off offset:2048 nt
	v_pk_fma_f32 v[50:51], v[50:51], v[72:73], v[56:57]
	v_lshlrev_b32_e32 v71, 16, v19
	v_lshlrev_b32_e32 v53, 16, v39
	v_lshlrev_b32_e32 v52, 16, v38
	v_pk_fma_f32 v[50:51], v[74:75], v[52:53], v[50:51]
	v_pk_mul_f32 v[52:53], v[100:101], v[58:59]
	v_and_b32_e32 v39, 0xffff0000, v39
	v_and_b32_e32 v38, 0xffff0000, v38
	v_lshlrev_b32_e32 v55, 16, v35
	v_lshlrev_b32_e32 v54, 16, v34
	v_pk_fma_f32 v[52:53], v[96:97], v[66:67], v[52:53]
	v_and_b32_e32 v35, 0xffff0000, v35
	v_and_b32_e32 v34, 0xffff0000, v34
	v_pk_mul_f32 v[50:51], v[50:51], v[54:55]
	v_pk_fma_f32 v[38:39], v[104:105], v[38:39], v[52:53]
	v_pk_mul_f32 v[54:55], v[120:121], v[64:65]
	v_pk_mul_f32 v[34:35], v[38:39], v[34:35]
	v_lshlrev_b32_e32 v39, 16, v41
	v_lshlrev_b32_e32 v38, 16, v40
	v_pk_fma_f32 v[54:55], v[118:119], v[78:79], v[54:55]
	v_lshlrev_b32_e32 v53, 16, v37
	v_lshlrev_b32_e32 v52, 16, v36
	v_pk_fma_f32 v[38:39], v[122:123], v[38:39], v[54:55]
	v_and_b32_e32 v41, 0xffff0000, v41
	v_pk_mul_f32 v[38:39], v[38:39], v[52:53]
	v_pk_mul_f32 v[52:53], v[92:93], v[60:61]
	v_and_b32_e32 v40, 0xffff0000, v40
	v_pk_fma_f32 v[52:53], v[84:85], v[68:69], v[52:53]
	v_and_b32_e32 v37, 0xffff0000, v37
	v_and_b32_e32 v36, 0xffff0000, v36
	v_pk_fma_f32 v[40:41], v[88:89], v[40:41], v[52:53]
	v_bfe_u32 v52, v35, 16, 1
	v_pk_mul_f32 v[36:37], v[40:41], v[36:37]
	v_bfe_u32 v53, v34, 16, 1
	v_bfe_u32 v40, v37, 16, 1
	v_bfe_u32 v41, v36, 16, 1
	v_add3_u32 v34, v34, v53, s5
	v_add3_u32 v35, v35, v52, s5
	v_add3_u32 v36, v36, v41, s5
	v_add3_u32 v37, v37, v40, s5
	v_bfe_u32 v40, v50, 16, 1
	v_bfe_u32 v41, v51, 16, 1
	v_bfe_u32 v52, v38, 16, 1
	v_bfe_u32 v53, v39, 16, 1
	v_add3_u32 v39, v39, v53, s5
	v_add3_u32 v38, v38, v52, s5
	v_add3_u32 v41, v51, v41, s5
	v_add3_u32 v40, v50, v40, s5
	v_lshrrev_b32_e32 v40, 16, v40
	v_lshrrev_b32_e32 v41, 16, v41
	v_lshrrev_b32_e32 v38, 16, v38
	v_lshrrev_b32_e32 v39, 16, v39
	v_and_or_b32 v37, v37, s1, v39
	v_and_or_b32 v36, v36, s1, v38
	v_and_or_b32 v35, v35, s1, v41
	v_and_or_b32 v34, v34, s1, v40
	global_store_dwordx4 v[148:149], v[34:37], off offset:2048 nt
	global_load_dwordx4 v[54:57], v[204:205], off
	global_load_dwordx4 v[58:61], v[206:207], off
	global_load_dwordx4 v[62:65], v[208:209], off
	s_nop 0
	global_load_dwordx4 v[34:37], v[204:205], off offset:16
	global_load_dwordx4 v[50:53], v[206:207], off offset:16
	global_load_dwordx4 v[38:41], v[208:209], off offset:16
	v_lshlrev_b32_e32 v67, 16, v23
	v_lshlrev_b32_e32 v66, 16, v22
	v_and_b32_e32 v69, 0xffff0000, v23
	v_and_b32_e32 v68, 0xffff0000, v22
	v_lshlrev_b32_e32 v70, 16, v18
	v_and_b32_e32 v73, 0xffff0000, v19
	v_and_b32_e32 v72, 0xffff0000, v18
	v_lshlrev_b32_e32 v75, 16, v47
	v_lshlrev_b32_e32 v74, 16, v46
	v_and_b32_e32 v77, 0xffff0000, v47
	v_and_b32_e32 v76, 0xffff0000, v46
	v_lshlrev_b32_e32 v47, 16, v43
	v_lshlrev_b32_e32 v46, 16, v42
	v_and_b32_e32 v79, 0xffff0000, v43
	v_and_b32_e32 v78, 0xffff0000, v42
	s_waitcnt vmcnt(5)
	v_mov_b32_e32 v18, v54
	s_waitcnt vmcnt(4)
	v_mov_b32_e32 v22, v58
	v_mov_b32_e32 v23, v60
	v_mov_b32_e32 v60, v59
	v_mov_b32_e32 v19, v56
	v_pk_mul_f32 v[42:43], v[22:23], v[70:71]
	v_mov_b32_e32 v56, v55
	v_pk_mul_f32 v[54:55], v[60:61], v[72:73]
	v_pk_fma_f32 v[66:67], v[18:19], v[66:67], v[42:43]
	s_waitcnt vmcnt(3)
	v_mov_b32_e32 v43, v64
	v_pk_fma_f32 v[54:55], v[56:57], v[68:69], v[54:55]
	v_mov_b32_e32 v64, v63
	v_mov_b32_e32 v42, v62
	v_pk_fma_f32 v[54:55], v[64:65], v[76:77], v[54:55]
	v_lshlrev_b32_e32 v63, 16, v21
	v_lshlrev_b32_e32 v62, 16, v20
	v_and_b32_e32 v21, 0xffff0000, v21
	v_and_b32_e32 v20, 0xffff0000, v20
	s_waitcnt vmcnt(1)
	v_mov_b32_e32 v80, v50
	v_mov_b32_e32 v81, v52
	v_mov_b32_e32 v52, v51
	v_pk_fma_f32 v[66:67], v[42:43], v[74:75], v[66:67]
	v_pk_mul_f32 v[54:55], v[54:55], v[78:79]
	v_lshlrev_b32_e32 v59, 16, v25
	v_lshlrev_b32_e32 v58, 16, v24
	v_and_b32_e32 v25, 0xffff0000, v25
	v_and_b32_e32 v24, 0xffff0000, v24
	v_mov_b32_e32 v78, v34
	v_mov_b32_e32 v79, v36
	v_pk_mul_f32 v[82:83], v[80:81], v[62:63]
	v_mov_b32_e32 v36, v35
	v_pk_mul_f32 v[34:35], v[52:53], v[20:21]
	v_pk_mul_f32 v[46:47], v[66:67], v[46:47]
	v_lshlrev_b32_e32 v67, 16, v49
	v_lshlrev_b32_e32 v66, 16, v48
	v_and_b32_e32 v49, 0xffff0000, v49
	v_and_b32_e32 v48, 0xffff0000, v48
	v_pk_fma_f32 v[58:59], v[78:79], v[58:59], v[82:83]
	s_waitcnt vmcnt(0)
	v_mov_b32_e32 v83, v40
	v_pk_fma_f32 v[24:25], v[36:37], v[24:25], v[34:35]
	v_mov_b32_e32 v40, v39
	v_lshlrev_b32_e32 v69, 16, v45
	v_lshlrev_b32_e32 v68, 16, v44
	v_and_b32_e32 v45, 0xffff0000, v45
	v_and_b32_e32 v44, 0xffff0000, v44
	v_mov_b32_e32 v82, v38
	v_pk_fma_f32 v[24:25], v[40:41], v[48:49], v[24:25]
	v_pk_fma_f32 v[58:59], v[82:83], v[66:67], v[58:59]
	v_pk_mul_f32 v[24:25], v[24:25], v[44:45]
	v_pk_mul_f32 v[58:59], v[58:59], v[68:69]
	v_bfe_u32 v34, v25, 16, 1
	v_bfe_u32 v35, v24, 16, 1
	v_add3_u32 v24, v24, v35, s5
	v_add3_u32 v25, v25, v34, s5
	v_bfe_u32 v34, v46, 16, 1
	v_bfe_u32 v35, v47, 16, 1
	v_bfe_u32 v44, v58, 16, 1
	v_bfe_u32 v45, v59, 16, 1
	v_bfe_u32 v38, v55, 16, 1
	v_bfe_u32 v39, v54, 16, 1
	v_add3_u32 v45, v59, v45, s5
	v_add3_u32 v44, v58, v44, s5
	v_add3_u32 v35, v47, v35, s5
	v_add3_u32 v34, v46, v34, s5
	v_add3_u32 v39, v54, v39, s5
	v_add3_u32 v38, v55, v38, s5
	v_lshrrev_b32_e32 v34, 16, v34
	v_lshrrev_b32_e32 v35, 16, v35
	v_lshrrev_b32_e32 v44, 16, v44
	v_lshrrev_b32_e32 v45, 16, v45
	v_and_or_b32 v47, v25, s1, v45
	v_and_or_b32 v46, v24, s1, v44
	v_and_or_b32 v45, v38, s1, v35
	v_and_or_b32 v44, v39, s1, v34
	v_pk_mul_f32 v[38:39], v[22:23], v[74:75]
	v_lshlrev_b32_e32 v35, 16, v31
	v_lshlrev_b32_e32 v34, 16, v30
	v_pk_fma_f32 v[38:39], v[18:19], v[70:71], v[38:39]
	v_lshlrev_b32_e32 v25, 16, v27
	v_lshlrev_b32_e32 v24, 16, v26
	v_pk_fma_f32 v[38:39], v[42:43], v[34:35], v[38:39]
	v_and_b32_e32 v31, 0xffff0000, v31
	v_pk_mul_f32 v[24:25], v[38:39], v[24:25]
	v_pk_mul_f32 v[38:39], v[60:61], v[76:77]
	v_and_b32_e32 v30, 0xffff0000, v30
	v_pk_fma_f32 v[38:39], v[56:57], v[72:73], v[38:39]
	global_store_dwordx4 v[146:147], v[44:47], off offset:3072 nt
	v_and_b32_e32 v27, 0xffff0000, v27
	v_and_b32_e32 v26, 0xffff0000, v26
	v_pk_fma_f32 v[38:39], v[64:65], v[30:31], v[38:39]
	v_pk_mul_f32 v[46:47], v[80:81], v[66:67]
	v_pk_mul_f32 v[26:27], v[38:39], v[26:27]
	v_lshlrev_b32_e32 v39, 16, v33
	v_lshlrev_b32_e32 v38, 16, v32
	v_pk_fma_f32 v[46:47], v[78:79], v[62:63], v[46:47]
	v_lshlrev_b32_e32 v45, 16, v29
	v_lshlrev_b32_e32 v44, 16, v28
	v_pk_fma_f32 v[46:47], v[82:83], v[38:39], v[46:47]
	v_and_b32_e32 v33, 0xffff0000, v33
	v_pk_mul_f32 v[44:45], v[46:47], v[44:45]
	v_pk_mul_f32 v[46:47], v[52:53], v[48:49]
	v_and_b32_e32 v32, 0xffff0000, v32
	v_pk_fma_f32 v[20:21], v[36:37], v[20:21], v[46:47]
	v_and_b32_e32 v29, 0xffff0000, v29
	v_and_b32_e32 v28, 0xffff0000, v28
	v_pk_fma_f32 v[20:21], v[40:41], v[32:33], v[20:21]
	v_bfe_u32 v46, v27, 16, 1
	v_pk_mul_f32 v[20:21], v[20:21], v[28:29]
	v_bfe_u32 v47, v26, 16, 1
	v_bfe_u32 v28, v21, 16, 1
	v_bfe_u32 v29, v20, 16, 1
	v_add3_u32 v47, v26, v47, s5
	v_add3_u32 v46, v27, v46, s5
	v_add3_u32 v20, v20, v29, s5
	v_add3_u32 v21, v21, v28, s5
	v_bfe_u32 v26, v24, 16, 1
	v_bfe_u32 v27, v25, 16, 1
	v_bfe_u32 v28, v44, 16, 1
	v_bfe_u32 v29, v45, 16, 1
	v_add3_u32 v29, v45, v29, s5
	v_add3_u32 v28, v44, v28, s5
	v_add3_u32 v25, v25, v27, s5
	v_add3_u32 v24, v24, v26, s5
	v_lshrrev_b32_e32 v24, 16, v24
	v_lshrrev_b32_e32 v25, 16, v25
	v_lshrrev_b32_e32 v26, 16, v28
	v_lshrrev_b32_e32 v27, 16, v29
	v_and_or_b32 v27, v21, s1, v27
	v_and_or_b32 v26, v20, s1, v26
	v_and_or_b32 v25, v46, s1, v25
	v_and_or_b32 v24, v47, s1, v24
	global_store_dwordx4 v[150:151], v[24:27], off offset:3072 nt
	v_lshlrev_b32_e32 v21, 16, v15
	v_lshlrev_b32_e32 v20, 16, v14
	v_pk_mul_f32 v[26:27], v[22:23], v[34:35]
	v_lshlrev_b32_e32 v25, 16, v11
	v_pk_fma_f32 v[26:27], v[18:19], v[74:75], v[26:27]
	v_lshlrev_b32_e32 v24, 16, v10
	v_pk_fma_f32 v[26:27], v[42:43], v[20:21], v[26:27]
	v_and_b32_e32 v15, 0xffff0000, v15
	v_pk_mul_f32 v[24:25], v[26:27], v[24:25]
	v_pk_mul_f32 v[26:27], v[60:61], v[30:31]
	v_and_b32_e32 v14, 0xffff0000, v14
	v_pk_fma_f32 v[26:27], v[56:57], v[76:77], v[26:27]
	v_and_b32_e32 v11, 0xffff0000, v11
	v_and_b32_e32 v10, 0xffff0000, v10
	v_pk_fma_f32 v[26:27], v[64:65], v[14:15], v[26:27]
	v_pk_mul_f32 v[44:45], v[80:81], v[38:39]
	v_pk_mul_f32 v[10:11], v[26:27], v[10:11]
	v_lshlrev_b32_e32 v27, 16, v17
	v_lshlrev_b32_e32 v26, 16, v16
	v_pk_fma_f32 v[44:45], v[78:79], v[66:67], v[44:45]
	v_lshlrev_b32_e32 v29, 16, v13
	v_lshlrev_b32_e32 v28, 16, v12
	v_pk_fma_f32 v[44:45], v[82:83], v[26:27], v[44:45]
	v_and_b32_e32 v17, 0xffff0000, v17
	v_pk_mul_f32 v[28:29], v[44:45], v[28:29]
	v_pk_mul_f32 v[44:45], v[52:53], v[32:33]
	v_and_b32_e32 v16, 0xffff0000, v16
	v_pk_fma_f32 v[44:45], v[36:37], v[48:49], v[44:45]
	v_and_b32_e32 v13, 0xffff0000, v13
	v_and_b32_e32 v12, 0xffff0000, v12
	v_pk_fma_f32 v[44:45], v[40:41], v[16:17], v[44:45]
	v_bfe_u32 v46, v11, 16, 1
	v_pk_mul_f32 v[12:13], v[44:45], v[12:13]
	v_bfe_u32 v47, v10, 16, 1
	v_bfe_u32 v44, v13, 16, 1
	v_bfe_u32 v45, v12, 16, 1
	v_add3_u32 v10, v10, v47, s5
	v_add3_u32 v11, v11, v46, s5
	v_add3_u32 v12, v12, v45, s5
	v_add3_u32 v13, v13, v44, s5
	v_bfe_u32 v44, v24, 16, 1
	v_bfe_u32 v45, v25, 16, 1
	v_bfe_u32 v46, v28, 16, 1
	v_bfe_u32 v47, v29, 16, 1
	v_add3_u32 v29, v29, v47, s5
	v_add3_u32 v28, v28, v46, s5
	v_add3_u32 v25, v25, v45, s5
	v_add3_u32 v24, v24, v44, s5
	v_lshrrev_b32_e32 v24, 16, v24
	v_lshrrev_b32_e32 v25, 16, v25
	v_lshrrev_b32_e32 v28, 16, v28
	v_lshrrev_b32_e32 v29, 16, v29
	v_and_or_b32 v13, v13, s1, v29
	v_and_or_b32 v12, v12, s1, v28
	v_and_or_b32 v11, v11, s1, v25
	v_and_or_b32 v10, v10, s1, v24
	v_pk_mul_f32 v[20:21], v[22:23], v[20:21]
	global_store_dwordx4 v[152:153], v[10:13], off offset:3072 nt
	v_pk_fma_f32 v[18:19], v[18:19], v[34:35], v[20:21]
	s_nop 0
	v_lshlrev_b32_e32 v11, 16, v7
	v_lshlrev_b32_e32 v10, 16, v6
	v_lshlrev_b32_e32 v13, 16, v3
	v_lshlrev_b32_e32 v12, 16, v2
	v_pk_fma_f32 v[10:11], v[42:43], v[10:11], v[18:19]
	v_and_b32_e32 v7, 0xffff0000, v7
	v_pk_mul_f32 v[10:11], v[10:11], v[12:13]
	v_pk_mul_f32 v[12:13], v[60:61], v[14:15]
	v_and_b32_e32 v6, 0xffff0000, v6
	v_pk_fma_f32 v[12:13], v[56:57], v[30:31], v[12:13]
	v_and_b32_e32 v3, 0xffff0000, v3
	v_and_b32_e32 v2, 0xffff0000, v2
	v_pk_fma_f32 v[6:7], v[64:65], v[6:7], v[12:13]
	v_pk_mul_f32 v[14:15], v[80:81], v[26:27]
	v_pk_mul_f32 v[2:3], v[6:7], v[2:3]
	v_lshlrev_b32_e32 v7, 16, v9
	v_lshlrev_b32_e32 v6, 16, v8
	v_pk_fma_f32 v[14:15], v[78:79], v[38:39], v[14:15]
	v_lshlrev_b32_e32 v13, 16, v5
	v_lshlrev_b32_e32 v12, 16, v4
	v_pk_fma_f32 v[6:7], v[82:83], v[6:7], v[14:15]
	v_and_b32_e32 v9, 0xffff0000, v9
	v_pk_mul_f32 v[6:7], v[6:7], v[12:13]
	v_pk_mul_f32 v[12:13], v[52:53], v[16:17]
	v_and_b32_e32 v8, 0xffff0000, v8
	v_pk_fma_f32 v[12:13], v[36:37], v[32:33], v[12:13]
	v_and_b32_e32 v5, 0xffff0000, v5
	v_and_b32_e32 v4, 0xffff0000, v4
	v_pk_fma_f32 v[8:9], v[40:41], v[8:9], v[12:13]
	v_bfe_u32 v12, v3, 16, 1
	v_pk_mul_f32 v[4:5], v[8:9], v[4:5]
	v_bfe_u32 v13, v2, 16, 1
	v_bfe_u32 v8, v5, 16, 1
	v_bfe_u32 v9, v4, 16, 1
	v_add3_u32 v2, v2, v13, s5
	v_add3_u32 v3, v3, v12, s5
	v_add3_u32 v4, v4, v9, s5
	v_add3_u32 v5, v5, v8, s5
	v_bfe_u32 v8, v10, 16, 1
	v_bfe_u32 v9, v11, 16, 1
	v_bfe_u32 v12, v6, 16, 1
	v_bfe_u32 v13, v7, 16, 1
	v_add3_u32 v7, v7, v13, s5
	v_add3_u32 v6, v6, v12, s5
	v_add3_u32 v9, v11, v9, s5
	v_add3_u32 v8, v10, v8, s5
	v_lshrrev_b32_e32 v8, 16, v8
	v_lshrrev_b32_e32 v9, 16, v9
	v_lshrrev_b32_e32 v6, 16, v6
	v_lshrrev_b32_e32 v7, 16, v7
	v_and_or_b32 v5, v5, s1, v7
	v_and_or_b32 v4, v4, s1, v6
	v_and_or_b32 v3, v3, s1, v9
	v_and_or_b32 v2, v2, s1, v8
	global_store_dwordx4 v[148:149], v[2:5], off offset:3072 nt
	s_cbranch_scc0 .LBB0_415

.LBB0_498:
	s_and_b32 s13, s95, 1
	s_cmp_lt_i32 s95, 2
	s_cselect_b32 s44, s59, s58
	s_lshl_b32 s0, s13, 7
	s_add_u32 s4, s87, s0
	s_addc_u32 s10, s88, 0
	s_waitcnt vmcnt(7) lgkmcnt(1)
	v_mov_b32_e32 v36, v0
	s_add_u32 s0, s89, s0
	s_addc_u32 s1, s90, 0
	v_readfirstlane_b32 s5, v36
	s_ashr_i32 s12, s5, 6
	s_lshl_b32 s45, s44, 8
	s_lshl_b32 s42, s12, 5
	s_add_i32 s38, s42, s45
	s_ashr_i32 s39, s38, 31
	v_and_b32_e32 v232, 63, v36
	s_lshl_b64 s[30:31], s[38:39], 12
	s_add_u32 s40, s4, s30
	v_lshlrev_b32_e32 v2, 12, v232
	s_addc_u32 s41, s10, s31
	s_waitcnt vmcnt(3)
	v_lshl_add_u64 v[4:5], s[0:1], 0, v[2:3]
	s_lshl_b32 s0, s12, 3
	s_ashr_i32 s1, s0, 31
	v_lshl_add_u64 v[224:225], s[0:1], 1, v[4:5]
	s_lshl_b32 s0, s12, 4
	v_bfe_u32 v2, v36, 2, 4
	v_and_or_b32 v2, s0, 48, v2
	s_ashr_i32 s0, s5, 3
	s_andn2_b32 s0, s0, 31
	v_lshlrev_b32_e32 v2, 12, v2
	s_ashr_i32 s1, s0, 31
	s_lshl_b32 s4, s12, 10
	v_lshl_add_u64 v[4:5], s[26:27], 0, v[2:3]
	v_lshlrev_b32_e32 v233, 3, v36
	s_cmp_lg_u32 0, -1
	v_lshl_add_u64 v[4:5], s[0:1], 1, v[4:5]
	v_and_b32_e32 v235, 24, v233
	s_cselect_b32 s0, 0, 0
	v_lshlrev_b32_e32 v2, 1, v235
	s_add_i32 s15, s4, s0
	s_mov_b32 s0, m0
	s_mov_b32 m0, s15
	s_nop 0
	global_load_lds_dwordx4 v[224:225], off
	s_mov_b32 m0, s0
	v_and_b32_e32 v234, 31, v36
	v_lshl_add_u64 v[226:227], v[4:5], 0, v[2:3]
	s_add_i32 s30, s15, 0x6000
	s_mov_b32 s0, m0
	s_mov_b32 m0, s30
	s_nop 0
	global_load_lds_dwordx4 v[226:227], off
	s_mov_b32 m0, s0
	v_bfe_u32 v218, v36, 5, 1
	v_lshl_add_u64 v[228:229], v[226:227], 0, s[16:17]
	s_add_i32 s0, s15, 0x8000
	s_mov_b32 s1, m0
	s_mov_b32 m0, s0
	s_nop 0
	global_load_lds_dwordx4 v[228:229], off
	s_mov_b32 m0, s1
	v_lshlrev_b32_e32 v2, 12, v234
	v_lshl_add_u64 v[4:5], v[224:225], 0, s[18:19]
	s_add_i32 s0, s15, 0x2000
	s_mov_b32 s1, m0
	s_mov_b32 m0, s0
	s_nop 0
	global_load_lds_dwordx4 v[4:5], off
	s_mov_b32 m0, s1
	v_lshl_or_b32 v2, v218, 4, v2
	global_load_dwordx4 v[174:177], v2, s[40:41] nt
	global_load_dwordx4 v[166:169], v2, s[40:41] offset:32 nt
	global_load_dwordx4 v[158:161], v2, s[40:41] offset:64 nt
	global_load_dwordx4 v[150:153], v2, s[40:41] offset:96 nt
	v_lshlrev_b32_e32 v2, 10, v218
	v_lshlrev_b32_e32 v4, 4, v234
	v_add3_u32 v240, 0, v2, v4
	v_lshl_add_u64 v[4:5], v[224:225], 0, s[20:21]
	s_add_i32 s0, s15, 0x4000
	s_mov_b32 s1, m0
	s_mov_b32 m0, s0
	s_nop 0
	global_load_lds_dwordx4 v[4:5], off
	s_mov_b32 m0, s1
	s_waitcnt vmcnt(3) lgkmcnt(0)
	s_barrier
	ds_read_b128 v[4:7], v240
	s_waitcnt vmcnt(4)
	ds_read_b128 v[8:11], v240 offset:512
	s_waitcnt vmcnt(10)
	ds_read_b128 v[38:41], v240 offset:2048
	s_waitcnt vmcnt(9)
	ds_read_b128 v[42:45], v240 offset:2560
	s_cmp_lg_u32 s44, 0
	s_cselect_b64 s[0:1], -1, 0
	v_or_b32_e32 v239, s42, v234
	s_and_b64 vcc, exec, s[0:1]
	s_waitcnt vmcnt(3) lgkmcnt(3)
	v_mfma_f32_32x32x16_bf16 v[20:35], v[4:7], v[174:177], 0
	s_waitcnt lgkmcnt(2)
	v_mfma_f32_32x32x16_bf16 v[4:19], v[8:11], v[174:177], 0
	s_waitcnt vmcnt(2) lgkmcnt(1)
	v_mfma_f32_32x32x16_bf16 v[20:35], v[38:41], v[166:169], v[20:35]
	s_waitcnt lgkmcnt(0)
	v_mfma_f32_32x32x16_bf16 v[4:19], v[42:45], v[166:169], v[4:19]
	ds_read_b128 v[38:41], v240 offset:4096
	ds_read_b128 v[42:45], v240 offset:4608
	s_waitcnt vmcnt(1) lgkmcnt(1)
	v_mfma_f32_32x32x16_bf16 v[20:35], v[38:41], v[158:161], v[20:35]
	s_waitcnt lgkmcnt(0)
	v_mfma_f32_32x32x16_bf16 v[4:19], v[42:45], v[158:161], v[4:19]
	ds_read_b128 v[38:41], v240 offset:6144
	ds_read_b128 v[42:45], v240 offset:6656
	s_waitcnt vmcnt(0) lgkmcnt(1)
	v_mfma_f32_32x32x16_bf16 v[20:35], v[38:41], v[150:153], v[20:35]
	s_waitcnt lgkmcnt(0)
	v_mfma_f32_32x32x16_bf16 v[4:19], v[42:45], v[150:153], v[4:19]
	s_nop 15
	s_nop 7
	s_cbranch_vccnz .LBB0_500
	v_lshlrev_b32_e32 v2, 2, v218
	v_or_b32_e32 v37, 32, v2
	v_cmp_le_i32_e32 vcc, v37, v239
	v_or_b32_e32 v37, 33, v2
	s_nop 6
	v_cndmask_b32_e32 v4, v231, v4, vcc
	v_cmp_lt_i32_e32 vcc, v2, v239
	s_nop 1
	v_cndmask_b32_e32 v21, v231, v21, vcc
	v_cmp_le_i32_e32 vcc, v2, v239
	s_nop 1
	v_cndmask_b32_e32 v20, v231, v20, vcc
	v_cmp_le_i32_e32 vcc, v37, v239
	v_or_b32_e32 v37, 2, v2
	s_nop 0
	v_cndmask_b32_e32 v5, v231, v5, vcc
	v_cmp_le_i32_e32 vcc, v37, v239
	v_or_b32_e32 v37, 34, v2
	s_nop 0
	v_cndmask_b32_e32 v22, v231, v22, vcc
	v_cmp_le_i32_e32 vcc, v37, v239
	v_or_b32_e32 v37, 3, v2
	s_nop 0
	v_cndmask_b32_e32 v6, v231, v6, vcc
	v_cmp_le_i32_e32 vcc, v37, v239
	v_or_b32_e32 v37, 35, v2
	s_nop 0
	v_cndmask_b32_e32 v23, v231, v23, vcc
	v_cmp_le_i32_e32 vcc, v37, v239
	v_or_b32_e32 v37, 8, v2
	s_nop 0
	v_cndmask_b32_e32 v7, v231, v7, vcc
	v_cmp_le_i32_e32 vcc, v37, v239
	v_or_b32_e32 v37, 40, v2
	s_nop 0
	v_cndmask_b32_e32 v24, v231, v24, vcc
	v_cmp_le_i32_e32 vcc, v37, v239
	v_or_b32_e32 v37, 9, v2
	s_nop 0
	v_cndmask_b32_e32 v8, v231, v8, vcc
	v_cmp_le_i32_e32 vcc, v37, v239
	v_or_b32_e32 v37, 41, v2
	s_nop 0
	v_cndmask_b32_e32 v25, v231, v25, vcc
	v_cmp_le_i32_e32 vcc, v37, v239
	v_or_b32_e32 v37, 10, v2
	s_nop 0
	v_cndmask_b32_e32 v9, v231, v9, vcc
	v_cmp_le_i32_e32 vcc, v37, v239
	v_or_b32_e32 v37, 42, v2
	s_nop 0
	v_cndmask_b32_e32 v26, v231, v26, vcc
	v_cmp_le_i32_e32 vcc, v37, v239
	v_or_b32_e32 v37, 11, v2
	s_nop 0
	v_cndmask_b32_e32 v10, v231, v10, vcc
	v_cmp_le_i32_e32 vcc, v37, v239
	v_or_b32_e32 v37, 43, v2
	s_nop 0
	v_cndmask_b32_e32 v27, v231, v27, vcc
	v_cmp_le_i32_e32 vcc, v37, v239
	v_or_b32_e32 v37, 16, v2
	s_nop 0
	v_cndmask_b32_e32 v11, v231, v11, vcc
	v_cmp_le_i32_e32 vcc, v37, v239
	v_or_b32_e32 v37, 48, v2
	s_nop 0
	v_cndmask_b32_e32 v28, v231, v28, vcc
	v_cmp_le_i32_e32 vcc, v37, v239
	v_or_b32_e32 v37, 17, v2
	s_nop 0
	v_cndmask_b32_e32 v12, v231, v12, vcc
	v_cmp_le_i32_e32 vcc, v37, v239
	v_or_b32_e32 v37, 49, v2
	s_nop 0
	v_cndmask_b32_e32 v29, v231, v29, vcc
	v_cmp_le_i32_e32 vcc, v37, v239
	v_or_b32_e32 v37, 18, v2
	s_nop 0
	v_cndmask_b32_e32 v13, v231, v13, vcc
	v_cmp_le_i32_e32 vcc, v37, v239
	v_or_b32_e32 v37, 50, v2
	s_nop 0
	v_cndmask_b32_e32 v30, v231, v30, vcc
	v_cmp_le_i32_e32 vcc, v37, v239
	v_or_b32_e32 v37, 19, v2
	s_nop 0
	v_cndmask_b32_e32 v14, v231, v14, vcc
	v_cmp_le_i32_e32 vcc, v37, v239
	v_or_b32_e32 v37, 51, v2
	s_nop 0
	v_cndmask_b32_e32 v31, v231, v31, vcc
	v_cmp_le_i32_e32 vcc, v37, v239
	v_or_b32_e32 v37, 24, v2
	s_nop 0
	v_cndmask_b32_e32 v15, v231, v15, vcc
	v_cmp_le_i32_e32 vcc, v37, v239
	v_or_b32_e32 v37, 56, v2
	s_nop 0
	v_cndmask_b32_e32 v32, v231, v32, vcc
	v_cmp_le_i32_e32 vcc, v37, v239
	v_or_b32_e32 v37, 25, v2
	s_nop 0
	v_cndmask_b32_e32 v16, v231, v16, vcc
	v_cmp_le_i32_e32 vcc, v37, v239
	v_or_b32_e32 v37, 57, v2
	s_nop 0
	v_cndmask_b32_e32 v33, v231, v33, vcc
	v_cmp_le_i32_e32 vcc, v37, v239
	v_or_b32_e32 v37, 26, v2
	s_nop 0
	v_cndmask_b32_e32 v17, v231, v17, vcc
	v_cmp_le_i32_e32 vcc, v37, v239
	v_or_b32_e32 v37, 58, v2
	s_nop 0
	v_cndmask_b32_e32 v34, v231, v34, vcc
	v_cmp_le_i32_e32 vcc, v37, v239
	v_or_b32_e32 v37, 27, v2
	v_or_b32_e32 v2, 59, v2
	v_cndmask_b32_e32 v18, v231, v18, vcc
	v_cmp_le_i32_e32 vcc, v37, v239
	s_nop 1
	v_cndmask_b32_e32 v35, v231, v35, vcc
	v_cmp_le_i32_e32 vcc, v2, v239
	s_nop 1
	v_cndmask_b32_e32 v19, v231, v19, vcc

.LBB0_544:
	s_waitcnt lgkmcnt(0)
	s_andn2_b64 vcc, exec, s[0:1]
	s_cbranch_vccnz .LBB0_497
	global_load_dword v44, v3, s[6:7]
	v_and_b32_e32 v2, 56, v233
	v_and_b32_e32 v24, 64, v1
	v_lshlrev_b32_e32 v104, 2, v2
	s_waitcnt lgkmcnt(3)
	v_lshlrev_b32_e32 v31, 16, v21
	v_lshlrev_b32_e32 v30, 16, v20
	v_and_b32_e32 v35, 0xffff0000, v21
	v_and_b32_e32 v34, 0xffff0000, v20
	v_lshlrev_b32_e32 v49, 16, v23
	v_lshlrev_b32_e32 v48, 16, v22
	v_and_b32_e32 v71, 0xffff0000, v23
	v_and_b32_e32 v70, 0xffff0000, v22
	v_add_u32_e32 v105, 64, v24
	global_load_dwordx4 v[20:23], v104, s[8:9] offset:16
	global_load_dwordx4 v[24:27], v104, s[8:9]
	v_xor_b32_e32 v45, 1, v1
	v_cmp_lt_i32_e32 vcc, v45, v105
	s_waitcnt vmcnt(7)
	v_lshlrev_b32_e32 v29, 16, v99
	v_lshlrev_b32_e32 v28, 16, v98
	v_cndmask_b32_e32 v45, v1, v45, vcc
	v_and_b32_e32 v33, 0xffff0000, v99
	v_and_b32_e32 v32, 0xffff0000, v98
	v_lshlrev_b32_e32 v47, 16, v101
	v_lshlrev_b32_e32 v46, 16, v100
	v_and_b32_e32 v69, 0xffff0000, v101
	v_and_b32_e32 v68, 0xffff0000, v100
	v_lshlrev_b32_e32 v76, 16, v97
	v_and_b32_e32 v77, 0xffff0000, v97
	v_lshlrev_b32_e32 v78, 16, v65
	v_and_b32_e32 v79, 0xffff0000, v65
	v_lshlrev_b32_e32 v80, 16, v96
	v_and_b32_e32 v81, 0xffff0000, v96
	v_lshlrev_b32_e32 v96, 16, v64
	v_and_b32_e32 v97, 0xffff0000, v64
	v_lshlrev_b32_e32 v64, 16, v95
	v_and_b32_e32 v65, 0xffff0000, v95
	v_lshlrev_b32_e32 v98, 16, v63
	v_and_b32_e32 v99, 0xffff0000, v63
	v_lshlrev_b32_e32 v100, 16, v94
	v_and_b32_e32 v101, 0xffff0000, v94
	v_lshlrev_b32_e32 v94, 16, v62
	v_and_b32_e32 v95, 0xffff0000, v62
	v_lshlrev_b32_e32 v45, 2, v45
	v_xor_b32_e32 v102, 2, v1
	v_cmp_lt_i32_e32 vcc, v102, v105
	v_xor_b32_e32 v103, 4, v1
	s_lshl_b64 s[0:1], s[38:39], 13
	s_add_u32 s0, s93, s0
	v_lshlrev_b32_e32 v2, 1, v2
	s_addc_u32 s1, s94, s1
	s_waitcnt vmcnt(2)
	v_pk_fma_f32 v[70:71], v[44:45], v[70:71], v[68:69] op_sel_hi:[0,1,1] neg_lo:[1,0,0] neg_hi:[1,0,0]
	v_pk_fma_f32 v[64:65], v[44:45], v[98:99], v[64:65] op_sel_hi:[0,1,1] neg_lo:[1,0,0] neg_hi:[1,0,0]
	v_pk_fma_f32 v[68:69], v[44:45], v[94:95], v[100:101] op_sel_hi:[0,1,1] neg_lo:[1,0,0] neg_hi:[1,0,0]
	v_pk_fma_f32 v[66:67], v[44:45], v[48:49], v[46:47] op_sel_hi:[0,1,1] neg_lo:[1,0,0] neg_hi:[1,0,0]
	v_pk_fma_f32 v[48:49], v[44:45], v[78:79], v[76:77] op_sel_hi:[0,1,1] neg_lo:[1,0,0] neg_hi:[1,0,0]
	v_pk_fma_f32 v[62:63], v[44:45], v[96:97], v[80:81] op_sel_hi:[0,1,1] neg_lo:[1,0,0] neg_hi:[1,0,0]
	v_pk_mul_f32 v[46:47], v[64:65], v[64:65]
	v_pk_mul_f32 v[76:77], v[68:69], v[68:69]
	v_pk_fma_f32 v[74:75], v[44:45], v[34:35], v[32:33] op_sel_hi:[0,1,1] neg_lo:[1,0,0] neg_hi:[1,0,0]
	v_pk_mul_f32 v[32:33], v[48:49], v[48:49]
	v_pk_mul_f32 v[34:35], v[62:63], v[62:63]
	v_add_f32_e32 v46, v46, v47
	v_add_f32_e32 v47, v76, v77
	v_add_f32_e32 v34, v34, v35
	v_add_f32_e32 v32, v32, v33
	v_add_f32_e32 v33, v47, v46
	v_pk_fma_f32 v[72:73], v[44:45], v[30:31], v[28:29] op_sel_hi:[0,1,1] neg_lo:[1,0,0] neg_hi:[1,0,0]
	v_pk_mul_f32 v[28:29], v[74:75], v[74:75]
	v_add_f32_e32 v33, v34, v33
	v_pk_fma_f32 v[28:29], v[72:73], v[72:73], v[28:29]
	v_add_f32_e32 v32, v32, v33
	v_pk_mul_f32 v[30:31], v[70:71], v[70:71]
	v_add_f32_e32 v28, v28, v32
	v_pk_fma_f32 v[30:31], v[66:67], v[66:67], v[30:31]
	v_add_f32_e32 v28, v29, v28
	v_add_f32_e32 v28, v30, v28
	v_add_f32_e32 v28, v31, v28
	ds_bpermute_b32 v29, v45, v28
	v_cndmask_b32_e32 v30, v1, v102, vcc
	v_lshlrev_b32_e32 v76, 2, v30
	v_cmp_lt_i32_e32 vcc, v103, v105
	v_lshlrev_b32_e32 v78, 10, v232
	s_waitcnt lgkmcnt(0)
	v_add_f32_e32 v28, v28, v29
	ds_bpermute_b32 v29, v76, v28
	v_cndmask_b32_e32 v30, v1, v103, vcc
	v_lshlrev_b32_e32 v77, 2, v30
	v_and_b32_e32 v95, 0xffff0000, v59
	v_lshlrev_b32_e32 v96, 16, v86
	s_waitcnt lgkmcnt(0)
	v_add_f32_e32 v46, v28, v29
	global_load_dwordx4 v[28:31], v104, s[8:9] offset:272
	global_load_dwordx4 v[32:35], v104, s[8:9] offset:256
	ds_bpermute_b32 v47, v77, v46
	v_and_b32_e32 v97, 0xffff0000, v86
	v_lshlrev_b32_e32 v86, 16, v58
	s_waitcnt lgkmcnt(0)
	v_add_f32_e32 v46, v46, v47
	v_fmamk_f32 v46, v46, 0x3c000000, v223
	v_mul_f32_e32 v47, 0x4f800000, v46
	v_cmp_gt_f32_e32 vcc, s35, v46
	s_nop 1
	v_cndmask_b32_e32 v79, v46, v47, vcc
	v_sqrt_f32_e32 v80, v79
	v_lshl_add_u64 v[46:47], s[0:1], 0, v[2:3]
	v_and_b32_e32 v2, 0xe000, v78
	v_lshl_add_u64 v[46:47], v[46:47], 0, v[2:3]
	v_add_u32_e32 v2, -1, v80
	v_add_u32_e32 v78, 1, v80
	v_fma_f32 v81, -v2, v80, v79
	v_fma_f32 v94, -v78, v80, v79
	v_cmp_ge_f32_e64 s[0:1], 0, v81
	s_nop 1
	v_cndmask_b32_e64 v2, v80, v2, s[0:1]
	v_cmp_lt_f32_e64 s[0:1], 0, v94
	s_nop 1
	v_cndmask_b32_e64 v2, v2, v78, s[0:1]
	v_mul_f32_e32 v78, 0x37800000, v2
	v_cndmask_b32_e32 v2, v2, v78, vcc
	v_cmp_class_f32_e32 vcc, v79, v230
	v_mov_b32_e32 v78, v72
	s_nop 0
	v_cndmask_b32_e32 v2, v2, v79, vcc
	v_div_scale_f32 v79, s[0:1], v2, v2, s54
	v_rcp_f32_e32 v80, v79
	v_div_scale_f32 v72, vcc, s54, v2, s54
	v_fma_f32 v81, -v79, v80, 1.0
	v_fmac_f32_e32 v80, v81, v80
	v_mul_f32_e32 v81, v72, v80
	v_fma_f32 v94, -v79, v81, v72
	v_fmac_f32_e32 v81, v94, v80
	v_fma_f32 v72, -v79, v81, v72
	v_div_fmas_f32 v72, v72, v80, v81
	v_div_fixup_f32 v2, v72, v2, s54
	v_pk_mul_f32 v[68:69], v[68:69], v[2:3] op_sel_hi:[1,0]
	v_pk_mul_f32 v[64:65], v[64:65], v[2:3] op_sel_hi:[1,0]
	v_pk_mul_f32 v[62:63], v[62:63], v[2:3] op_sel_hi:[1,0]
	v_pk_mul_f32 v[48:49], v[48:49], v[2:3] op_sel_hi:[1,0]
	s_waitcnt vmcnt(2)
	v_pk_mul_f32 v[68:69], v[24:25], v[68:69]
	v_pk_mul_f32 v[64:65], v[26:27], v[64:65]
	v_pk_mul_f32 v[80:81], v[20:21], v[62:63]
	v_pk_mul_f32 v[48:49], v[22:23], v[48:49]
	v_cvt_pk_bf16_f32 v62, v68, v69
	v_cvt_pk_bf16_f32 v63, v64, v65
	v_cvt_pk_bf16_f32 v64, v80, v81
	v_cvt_pk_bf16_f32 v65, v48, v49
	global_store_dwordx4 v[46:47], v[62:65], off nt
	v_lshlrev_b32_e32 v49, 16, v91
	v_lshlrev_b32_e32 v48, 16, v90
	v_lshlrev_b32_e32 v63, 16, v41
	v_lshlrev_b32_e32 v62, 16, v40
	v_pk_fma_f32 v[48:49], v[44:45], v[62:63], v[48:49] op_sel_hi:[0,1,1] neg_lo:[1,0,0] neg_hi:[1,0,0]
	v_and_b32_e32 v63, 0xffff0000, v91
	v_and_b32_e32 v62, 0xffff0000, v90
	v_and_b32_e32 v41, 0xffff0000, v41
	v_and_b32_e32 v40, 0xffff0000, v40
	v_pk_fma_f32 v[64:65], v[44:45], v[40:41], v[62:63] op_sel_hi:[0,1,1] neg_lo:[1,0,0] neg_hi:[1,0,0]
	v_lshlrev_b32_e32 v63, 16, v93
	v_lshlrev_b32_e32 v62, 16, v92
	v_lshlrev_b32_e32 v69, 16, v43
	v_lshlrev_b32_e32 v68, 16, v42
	v_pk_fma_f32 v[62:63], v[44:45], v[68:69], v[62:63] op_sel_hi:[0,1,1] neg_lo:[1,0,0] neg_hi:[1,0,0]
	v_and_b32_e32 v69, 0xffff0000, v93
	v_and_b32_e32 v68, 0xffff0000, v92
	v_lshlrev_b32_e32 v80, 16, v89
	v_and_b32_e32 v81, 0xffff0000, v89
	v_lshlrev_b32_e32 v92, 16, v88
	v_and_b32_e32 v93, 0xffff0000, v88
	v_lshlrev_b32_e32 v88, 16, v60
	v_and_b32_e32 v89, 0xffff0000, v60
	v_lshlrev_b32_e32 v90, 16, v61
	v_and_b32_e32 v91, 0xffff0000, v61
	v_pk_fma_f32 v[60:61], v[44:45], v[88:89], v[92:93] op_sel_hi:[0,1,1] neg_lo:[1,0,0] neg_hi:[1,0,0]
	v_lshlrev_b32_e32 v92, 16, v87
	v_and_b32_e32 v93, 0xffff0000, v87
	v_lshlrev_b32_e32 v94, 16, v59
	v_and_b32_e32 v87, 0xffff0000, v58
	v_pk_fma_f32 v[92:93], v[44:45], v[94:95], v[92:93] op_sel_hi:[0,1,1] neg_lo:[1,0,0] neg_hi:[1,0,0]
	v_pk_fma_f32 v[58:59], v[44:45], v[86:87], v[96:97] op_sel_hi:[0,1,1] neg_lo:[1,0,0] neg_hi:[1,0,0]
	v_pk_mul_f32 v[94:95], v[92:93], v[92:93]
	v_pk_mul_f32 v[86:87], v[58:59], v[58:59]
	v_pk_fma_f32 v[80:81], v[44:45], v[90:91], v[80:81] op_sel_hi:[0,1,1] neg_lo:[1,0,0] neg_hi:[1,0,0]
	v_pk_mul_f32 v[88:89], v[60:61], v[60:61]
	v_add_f32_e32 v72, v94, v95
	v_add_f32_e32 v79, v86, v87
	v_pk_mul_f32 v[90:91], v[80:81], v[80:81]
	v_add_f32_e32 v72, v79, v72
	v_add_f32_e32 v79, v88, v89
	v_pk_mul_f32 v[40:41], v[64:65], v[64:65]
	v_and_b32_e32 v43, 0xffff0000, v43
	v_and_b32_e32 v42, 0xffff0000, v42
	v_add_f32_e32 v72, v79, v72
	v_add_f32_e32 v79, v90, v91
	v_pk_fma_f32 v[40:41], v[48:49], v[48:49], v[40:41]
	v_pk_fma_f32 v[68:69], v[44:45], v[42:43], v[68:69] op_sel_hi:[0,1,1] neg_lo:[1,0,0] neg_hi:[1,0,0]
	v_add_f32_e32 v72, v79, v72
	v_pk_mul_f32 v[42:43], v[68:69], v[68:69]
	v_add_f32_e32 v40, v40, v72
	v_pk_fma_f32 v[42:43], v[62:63], v[62:63], v[42:43]
	v_add_f32_e32 v40, v41, v40
	v_add_f32_e32 v40, v42, v40
	v_add_f32_e32 v42, v43, v40
	ds_bpermute_b32 v43, v45, v42
	v_mov_b32_e32 v79, v74
	v_pk_mul_f32 v[40:41], v[78:79], v[2:3] op_sel_hi:[1,0]
	v_mov_b32_e32 v74, v73
	s_waitcnt vmcnt(1)
	v_pk_mul_f32 v[40:41], v[32:33], v[40:41]
	s_waitcnt lgkmcnt(0)
	v_add_f32_e32 v72, v42, v43
	ds_bpermute_b32 v78, v76, v72
	v_pk_mul_f32 v[42:43], v[74:75], v[2:3] op_sel_hi:[1,0]
	v_cvt_pk_bf16_f32 v40, v40, v41
	v_pk_mul_f32 v[42:43], v[34:35], v[42:43]
	v_and_b32_e32 v79, 0xffff0000, v14
	s_waitcnt lgkmcnt(0)
	v_add_f32_e32 v72, v72, v78
	ds_bpermute_b32 v73, v77, v72
	v_cvt_pk_bf16_f32 v41, v42, v43
	v_mov_b32_e32 v42, v66
	v_mov_b32_e32 v43, v70
	v_pk_mul_f32 v[42:43], v[42:43], v[2:3] op_sel_hi:[1,0]
	s_waitcnt lgkmcnt(0)
	v_add_f32_e32 v66, v72, v73
	v_fmamk_f32 v66, v66, 0x3c000000, v223
	v_mul_f32_e32 v70, 0x4f800000, v66
	v_cmp_gt_f32_e32 vcc, s35, v66
	v_pk_mul_f32 v[42:43], v[28:29], v[42:43]
	v_lshlrev_b32_e32 v78, 16, v14
	v_cndmask_b32_e32 v72, v66, v70, vcc
	v_sqrt_f32_e32 v73, v72
	v_mov_b32_e32 v70, v67
	v_pk_mul_f32 v[66:67], v[70:71], v[2:3] op_sel_hi:[1,0]
	v_cvt_pk_bf16_f32 v42, v42, v43
	v_add_u32_e32 v2, -1, v73
	v_fma_f32 v43, -v2, v73, v72
	v_cmp_ge_f32_e64 s[0:1], 0, v43
	v_add_u32_e32 v43, 1, v73
	v_fma_f32 v70, -v43, v73, v72
	v_cndmask_b32_e64 v2, v73, v2, s[0:1]
	v_cmp_lt_f32_e64 s[0:1], 0, v70
	v_pk_mul_f32 v[66:67], v[30:31], v[66:67]
	v_and_b32_e32 v73, 0xffff0000, v15
	v_cndmask_b32_e64 v2, v2, v43, s[0:1]
	v_mul_f32_e32 v43, 0x37800000, v2
	v_cndmask_b32_e32 v2, v2, v43, vcc
	v_cmp_class_f32_e32 vcc, v72, v230
	v_cvt_pk_bf16_f32 v43, v66, v67
	global_store_dwordx4 v[46:47], v[40:43], off offset:128 nt
	v_cndmask_b32_e32 v2, v2, v72, vcc
	v_div_scale_f32 v70, s[0:1], v2, v2, s54
	v_rcp_f32_e32 v71, v70
	s_mov_b32 s0, 0x10000
	v_lshlrev_b32_e32 v72, 16, v15
	v_lshlrev_b32_e32 v14, 16, v56
	v_fma_f32 v40, -v70, v71, 1.0
	v_fmac_f32_e32 v71, v40, v71
	v_div_scale_f32 v40, vcc, s54, v2, s54
	v_mul_f32_e32 v41, v40, v71
	v_fma_f32 v42, -v70, v41, v40
	v_fmac_f32_e32 v41, v42, v71
	v_fma_f32 v40, -v70, v41, v40
	v_div_fmas_f32 v40, v40, v71, v41
	v_div_fixup_f32 v2, v40, v2, s54
	v_pk_mul_f32 v[40:41], v[58:59], v[2:3] op_sel_hi:[1,0]
	v_pk_mul_f32 v[42:43], v[92:93], v[2:3] op_sel_hi:[1,0]
	v_pk_mul_f32 v[40:41], v[24:25], v[40:41]
	v_pk_mul_f32 v[42:43], v[26:27], v[42:43]
	v_cvt_pk_bf16_f32 v40, v40, v41
	v_cvt_pk_bf16_f32 v41, v42, v43
	v_pk_mul_f32 v[42:43], v[60:61], v[2:3] op_sel_hi:[1,0]
	v_pk_mul_f32 v[58:59], v[80:81], v[2:3] op_sel_hi:[1,0]
	v_pk_mul_f32 v[42:43], v[20:21], v[42:43]
	v_pk_mul_f32 v[58:59], v[22:23], v[58:59]
	v_cvt_pk_bf16_f32 v42, v42, v43
	v_cvt_pk_bf16_f32 v43, v58, v59
	v_add_co_u32_e32 v58, vcc, s0, v46
	v_and_b32_e32 v15, 0xffff0000, v56
	s_nop 0
	v_addc_co_u32_e32 v59, vcc, 0, v47, vcc
	global_store_dwordx4 v[58:59], v[40:43], off nt
	v_lshlrev_b32_e32 v74, 16, v57
	v_and_b32_e32 v75, 0xffff0000, v57
	v_lshlrev_b32_e32 v41, 16, v83
	v_lshlrev_b32_e32 v40, 16, v82
	v_lshlrev_b32_e32 v43, 16, v37
	v_lshlrev_b32_e32 v42, 16, v36
	v_pk_fma_f32 v[40:41], v[44:45], v[42:43], v[40:41] op_sel_hi:[0,1,1] neg_lo:[1,0,0] neg_hi:[1,0,0]
	v_and_b32_e32 v43, 0xffff0000, v83
	v_and_b32_e32 v42, 0xffff0000, v82
	v_pk_fma_f32 v[56:57], v[44:45], v[14:15], v[78:79] op_sel_hi:[0,1,1] neg_lo:[1,0,0] neg_hi:[1,0,0]
	v_lshlrev_b32_e32 v78, 16, v13
	v_and_b32_e32 v79, 0xffff0000, v13
	v_lshlrev_b32_e32 v80, 16, v55
	v_and_b32_e32 v81, 0xffff0000, v55
	v_lshlrev_b32_e32 v82, 16, v12
	v_and_b32_e32 v83, 0xffff0000, v12
	v_lshlrev_b32_e32 v12, 16, v54
	v_and_b32_e32 v13, 0xffff0000, v54
	v_and_b32_e32 v37, 0xffff0000, v37
	v_and_b32_e32 v36, 0xffff0000, v36
	v_pk_fma_f32 v[78:79], v[44:45], v[80:81], v[78:79] op_sel_hi:[0,1,1] neg_lo:[1,0,0] neg_hi:[1,0,0]
	v_pk_fma_f32 v[54:55], v[44:45], v[12:13], v[82:83] op_sel_hi:[0,1,1] neg_lo:[1,0,0] neg_hi:[1,0,0]
	v_pk_fma_f32 v[42:43], v[44:45], v[36:37], v[42:43] op_sel_hi:[0,1,1] neg_lo:[1,0,0] neg_hi:[1,0,0]
	v_pk_mul_f32 v[80:81], v[78:79], v[78:79]
	v_pk_mul_f32 v[12:13], v[54:55], v[54:55]
	v_mov_b32_e32 v60, v48
	v_pk_mul_f32 v[36:37], v[42:43], v[42:43]
	v_pk_fma_f32 v[72:73], v[44:45], v[74:75], v[72:73] op_sel_hi:[0,1,1] neg_lo:[1,0,0] neg_hi:[1,0,0]
	v_pk_mul_f32 v[14:15], v[56:57], v[56:57]
	v_add_f32_e32 v48, v80, v81
	v_add_f32_e32 v12, v12, v13
	v_pk_fma_f32 v[66:67], v[40:41], v[40:41], v[36:37]
	v_lshlrev_b32_e32 v37, 16, v85
	v_lshlrev_b32_e32 v36, 16, v84
	v_lshlrev_b32_e32 v71, 16, v39
	v_lshlrev_b32_e32 v70, 16, v38
	v_pk_mul_f32 v[74:75], v[72:73], v[72:73]
	v_add_f32_e32 v12, v12, v48
	v_add_f32_e32 v13, v14, v15
	v_pk_fma_f32 v[36:37], v[44:45], v[70:71], v[36:37] op_sel_hi:[0,1,1] neg_lo:[1,0,0] neg_hi:[1,0,0]
	v_and_b32_e32 v71, 0xffff0000, v85
	v_and_b32_e32 v70, 0xffff0000, v84
	v_and_b32_e32 v39, 0xffff0000, v39
	v_and_b32_e32 v38, 0xffff0000, v38
	v_add_f32_e32 v12, v13, v12
	v_add_f32_e32 v13, v74, v75
	v_pk_fma_f32 v[38:39], v[44:45], v[38:39], v[70:71] op_sel_hi:[0,1,1] neg_lo:[1,0,0] neg_hi:[1,0,0]
	v_add_f32_e32 v12, v13, v12
	v_pk_mul_f32 v[70:71], v[38:39], v[38:39]
	v_add_f32_e32 v12, v66, v12
	v_pk_fma_f32 v[70:71], v[36:37], v[36:37], v[70:71]
	v_add_f32_e32 v12, v67, v12
	v_add_f32_e32 v12, v70, v12
	v_add_f32_e32 v14, v71, v12
	ds_bpermute_b32 v15, v45, v14
	v_mov_b32_e32 v61, v64
	v_pk_mul_f32 v[12:13], v[60:61], v[2:3] op_sel_hi:[1,0]
	v_mov_b32_e32 v64, v49
	v_pk_mul_f32 v[12:13], v[32:33], v[12:13]
	s_waitcnt lgkmcnt(0)
	v_add_f32_e32 v48, v14, v15
	ds_bpermute_b32 v60, v76, v48
	v_pk_mul_f32 v[14:15], v[64:65], v[2:3] op_sel_hi:[1,0]
	v_cvt_pk_bf16_f32 v12, v12, v13
	v_pk_mul_f32 v[14:15], v[34:35], v[14:15]
	v_lshlrev_b32_e32 v64, 16, v4
	s_waitcnt lgkmcnt(0)
	v_add_f32_e32 v48, v48, v60
	ds_bpermute_b32 v49, v77, v48
	v_cvt_pk_bf16_f32 v13, v14, v15
	v_mov_b32_e32 v14, v62
	v_mov_b32_e32 v15, v68
	v_pk_mul_f32 v[14:15], v[14:15], v[2:3] op_sel_hi:[1,0]
	s_waitcnt lgkmcnt(0)
	v_add_f32_e32 v48, v48, v49
	v_fmamk_f32 v48, v48, 0x3c000000, v223
	v_mul_f32_e32 v49, 0x4f800000, v48
	v_cmp_gt_f32_e32 vcc, s35, v48
	v_mov_b32_e32 v68, v63
	v_pk_mul_f32 v[14:15], v[28:29], v[14:15]
	v_cndmask_b32_e32 v60, v48, v49, vcc
	v_sqrt_f32_e32 v61, v60
	v_pk_mul_f32 v[48:49], v[68:69], v[2:3] op_sel_hi:[1,0]
	v_cvt_pk_bf16_f32 v14, v14, v15
	v_pk_mul_f32 v[48:49], v[30:31], v[48:49]
	v_add_u32_e32 v2, -1, v61
	v_fma_f32 v15, -v2, v61, v60
	v_cmp_ge_f32_e64 s[0:1], 0, v15
	v_add_u32_e32 v15, 1, v61
	v_lshlrev_b32_e32 v62, 16, v51
	v_cndmask_b32_e64 v2, v61, v2, s[0:1]
	v_fma_f32 v61, -v15, v61, v60
	v_cmp_lt_f32_e64 s[0:1], 0, v61
	v_and_b32_e32 v63, 0xffff0000, v51
	v_and_b32_e32 v65, 0xffff0000, v4
	v_cndmask_b32_e64 v2, v2, v15, s[0:1]
	v_mul_f32_e32 v15, 0x37800000, v2
	v_cndmask_b32_e32 v2, v2, v15, vcc
	v_cmp_class_f32_e32 vcc, v60, v230
	v_cvt_pk_bf16_f32 v15, v48, v49
	global_store_dwordx4 v[58:59], v[12:15], off offset:128 nt
	v_cndmask_b32_e32 v2, v2, v60, vcc
	v_div_scale_f32 v60, s[0:1], v2, v2, s54
	v_rcp_f32_e32 v61, v60
	s_mov_b32 s0, 0x20000
	v_lshlrev_b32_e32 v58, 16, v53
	v_and_b32_e32 v59, 0xffff0000, v53
	v_fma_f32 v12, -v60, v61, 1.0
	v_fmac_f32_e32 v61, v12, v61
	v_div_scale_f32 v12, vcc, s54, v2, s54
	v_mul_f32_e32 v13, v12, v61
	v_fma_f32 v14, -v60, v13, v12
	v_fmac_f32_e32 v13, v14, v61
	v_fma_f32 v12, -v60, v13, v12
	v_div_fmas_f32 v12, v12, v61, v13
	v_div_fixup_f32 v2, v12, v2, s54
	v_pk_mul_f32 v[12:13], v[54:55], v[2:3] op_sel_hi:[1,0]
	v_pk_mul_f32 v[14:15], v[78:79], v[2:3] op_sel_hi:[1,0]
	v_pk_mul_f32 v[12:13], v[24:25], v[12:13]
	v_pk_mul_f32 v[14:15], v[26:27], v[14:15]
	v_cvt_pk_bf16_f32 v12, v12, v13
	v_cvt_pk_bf16_f32 v13, v14, v15
	v_pk_mul_f32 v[14:15], v[56:57], v[2:3] op_sel_hi:[1,0]
	v_pk_mul_f32 v[48:49], v[72:73], v[2:3] op_sel_hi:[1,0]
	v_pk_mul_f32 v[14:15], v[20:21], v[14:15]
	v_pk_mul_f32 v[48:49], v[22:23], v[48:49]
	v_cvt_pk_bf16_f32 v14, v14, v15
	v_cvt_pk_bf16_f32 v15, v48, v49
	v_add_co_u32_e32 v48, vcc, s0, v46
	v_lshlrev_b32_e32 v55, 16, v17
	s_nop 0
	v_addc_co_u32_e32 v49, vcc, 0, v47, vcc
	global_store_dwordx4 v[48:49], v[12:15], off nt
	v_lshlrev_b32_e32 v54, 16, v16
	v_lshlrev_b32_e32 v57, 16, v19
	v_lshlrev_b32_e32 v15, 16, v9
	v_lshlrev_b32_e32 v14, 16, v8
	v_pk_fma_f32 v[14:15], v[44:45], v[54:55], v[14:15] op_sel_hi:[0,1,1] neg_lo:[1,0,0] neg_hi:[1,0,0]
	v_lshlrev_b32_e32 v55, 16, v11
	v_lshlrev_b32_e32 v54, 16, v10
	v_lshlrev_b32_e32 v56, 16, v18
	v_pk_fma_f32 v[54:55], v[44:45], v[56:57], v[54:55] op_sel_hi:[0,1,1] neg_lo:[1,0,0] neg_hi:[1,0,0]
	v_lshlrev_b32_e32 v56, 16, v7
	v_and_b32_e32 v57, 0xffff0000, v7
	v_lshlrev_b32_e32 v60, 16, v6
	v_and_b32_e32 v61, 0xffff0000, v6
	v_lshlrev_b32_e32 v6, 16, v52
	v_and_b32_e32 v7, 0xffff0000, v52
	v_pk_fma_f32 v[52:53], v[44:45], v[6:7], v[60:61] op_sel_hi:[0,1,1] neg_lo:[1,0,0] neg_hi:[1,0,0]
	v_lshlrev_b32_e32 v60, 16, v5
	v_and_b32_e32 v61, 0xffff0000, v5
	v_lshlrev_b32_e32 v4, 16, v50
	v_and_b32_e32 v5, 0xffff0000, v50
	v_pk_fma_f32 v[60:61], v[44:45], v[62:63], v[60:61] op_sel_hi:[0,1,1] neg_lo:[1,0,0] neg_hi:[1,0,0]
	v_pk_fma_f32 v[50:51], v[44:45], v[4:5], v[64:65] op_sel_hi:[0,1,1] neg_lo:[1,0,0] neg_hi:[1,0,0]
	v_pk_mul_f32 v[62:63], v[60:61], v[60:61]
	v_pk_mul_f32 v[4:5], v[50:51], v[50:51]
	v_and_b32_e32 v9, 0xffff0000, v9
	v_and_b32_e32 v8, 0xffff0000, v8
	v_and_b32_e32 v17, 0xffff0000, v17
	v_and_b32_e32 v16, 0xffff0000, v16
	v_pk_fma_f32 v[56:57], v[44:45], v[58:59], v[56:57] op_sel_hi:[0,1,1] neg_lo:[1,0,0] neg_hi:[1,0,0]
	v_pk_mul_f32 v[6:7], v[52:53], v[52:53]
	v_add_f32_e32 v13, v62, v63
	v_add_f32_e32 v4, v4, v5
	v_pk_fma_f32 v[8:9], v[44:45], v[16:17], v[8:9] op_sel_hi:[0,1,1] neg_lo:[1,0,0] neg_hi:[1,0,0]
	v_pk_mul_f32 v[58:59], v[56:57], v[56:57]
	v_add_f32_e32 v4, v4, v13
	v_add_f32_e32 v5, v6, v7
	v_pk_mul_f32 v[16:17], v[8:9], v[8:9]
	v_and_b32_e32 v11, 0xffff0000, v11
	v_and_b32_e32 v10, 0xffff0000, v10
	v_and_b32_e32 v19, 0xffff0000, v19
	v_and_b32_e32 v18, 0xffff0000, v18
	v_add_f32_e32 v4, v5, v4
	v_add_f32_e32 v5, v58, v59
	v_pk_fma_f32 v[16:17], v[14:15], v[14:15], v[16:17]
	v_pk_fma_f32 v[10:11], v[44:45], v[18:19], v[10:11] op_sel_hi:[0,1,1] neg_lo:[1,0,0] neg_hi:[1,0,0]
	v_add_f32_e32 v4, v5, v4
	v_pk_mul_f32 v[18:19], v[10:11], v[10:11]
	v_add_f32_e32 v4, v16, v4
	v_pk_fma_f32 v[18:19], v[54:55], v[54:55], v[18:19]
	v_add_f32_e32 v4, v17, v4
	v_add_f32_e32 v4, v18, v4
	v_add_f32_e32 v6, v19, v4
	ds_bpermute_b32 v7, v45, v6
	v_mov_b32_e32 v12, v40
	v_mov_b32_e32 v13, v42
	v_pk_mul_f32 v[4:5], v[12:13], v[2:3] op_sel_hi:[1,0]
	v_mov_b32_e32 v42, v41
	s_waitcnt lgkmcnt(0)
	v_add_f32_e32 v12, v6, v7
	ds_bpermute_b32 v13, v76, v12
	v_pk_mul_f32 v[6:7], v[42:43], v[2:3] op_sel_hi:[1,0]
	v_pk_mul_f32 v[4:5], v[32:33], v[4:5]
	v_pk_mul_f32 v[6:7], v[34:35], v[6:7]
	v_cvt_pk_bf16_f32 v4, v4, v5
	s_waitcnt lgkmcnt(0)
	v_add_f32_e32 v12, v12, v13
	ds_bpermute_b32 v13, v77, v12
	v_cvt_pk_bf16_f32 v5, v6, v7
	v_mov_b32_e32 v6, v36
	v_mov_b32_e32 v7, v38
	v_pk_mul_f32 v[6:7], v[6:7], v[2:3] op_sel_hi:[1,0]
	s_waitcnt lgkmcnt(0)
	v_add_f32_e32 v12, v12, v13
	v_fmamk_f32 v12, v12, 0x3c000000, v223
	v_mul_f32_e32 v13, 0x4f800000, v12
	v_cmp_gt_f32_e32 vcc, s35, v12
	v_mov_b32_e32 v38, v37
	v_pk_mul_f32 v[6:7], v[28:29], v[6:7]
	v_cndmask_b32_e32 v16, v12, v13, vcc
	v_sqrt_f32_e32 v17, v16
	v_pk_mul_f32 v[12:13], v[38:39], v[2:3] op_sel_hi:[1,0]
	v_cvt_pk_bf16_f32 v6, v6, v7
	v_pk_mul_f32 v[12:13], v[30:31], v[12:13]
	v_add_u32_e32 v2, -1, v17
	v_fma_f32 v7, -v2, v17, v16
	v_cmp_ge_f32_e64 s[0:1], 0, v7
	v_add_u32_e32 v7, 1, v17
	s_nop 0
	v_cndmask_b32_e64 v2, v17, v2, s[0:1]
	v_fma_f32 v17, -v7, v17, v16
	v_cmp_lt_f32_e64 s[0:1], 0, v17
	s_nop 1
	v_cndmask_b32_e64 v2, v2, v7, s[0:1]
	v_mul_f32_e32 v7, 0x37800000, v2
	v_cndmask_b32_e32 v2, v2, v7, vcc
	v_cmp_class_f32_e32 vcc, v16, v230
	v_cvt_pk_bf16_f32 v7, v12, v13
	global_store_dwordx4 v[48:49], v[4:7], off offset:128 nt
	v_cndmask_b32_e32 v2, v2, v16, vcc
	v_div_scale_f32 v16, s[0:1], v2, v2, s54
	v_rcp_f32_e32 v17, v16
	s_mov_b32 s0, 0x30000
	v_fma_f32 v4, -v16, v17, 1.0
	v_fmac_f32_e32 v17, v4, v17
	v_div_scale_f32 v4, vcc, s54, v2, s54
	v_mul_f32_e32 v5, v4, v17
	v_fma_f32 v6, -v16, v5, v4
	v_fmac_f32_e32 v5, v6, v17
	v_fma_f32 v4, -v16, v5, v4
	v_div_fmas_f32 v4, v4, v17, v5
	v_div_fixup_f32 v2, v4, v2, s54
	v_pk_mul_f32 v[4:5], v[50:51], v[2:3] op_sel_hi:[1,0]
	v_pk_mul_f32 v[6:7], v[60:61], v[2:3] op_sel_hi:[1,0]
	v_pk_mul_f32 v[4:5], v[24:25], v[4:5]
	v_pk_mul_f32 v[6:7], v[26:27], v[6:7]
	v_cvt_pk_bf16_f32 v4, v4, v5
	v_cvt_pk_bf16_f32 v5, v6, v7
	v_pk_mul_f32 v[6:7], v[52:53], v[2:3] op_sel_hi:[1,0]
	v_pk_mul_f32 v[12:13], v[56:57], v[2:3] op_sel_hi:[1,0]
	v_pk_mul_f32 v[6:7], v[20:21], v[6:7]
	v_pk_mul_f32 v[12:13], v[22:23], v[12:13]
	v_cvt_pk_bf16_f32 v6, v6, v7
	v_cvt_pk_bf16_f32 v7, v12, v13
	v_add_co_u32_e32 v12, vcc, s0, v46
	s_nop 1
	v_addc_co_u32_e32 v13, vcc, 0, v47, vcc
	global_store_dwordx4 v[12:13], v[4:7], off nt
	s_nop 1
	v_mov_b32_e32 v4, v14
	v_mov_b32_e32 v5, v8
	v_mov_b32_e32 v8, v15
	v_pk_mul_f32 v[4:5], v[4:5], v[2:3] op_sel_hi:[1,0]
	v_pk_mul_f32 v[6:7], v[8:9], v[2:3] op_sel_hi:[1,0]
	v_pk_mul_f32 v[4:5], v[32:33], v[4:5]
	v_pk_mul_f32 v[6:7], v[34:35], v[6:7]
	v_cvt_pk_bf16_f32 v4, v4, v5
	v_cvt_pk_bf16_f32 v5, v6, v7
	v_mov_b32_e32 v6, v54
	v_mov_b32_e32 v7, v10
	v_mov_b32_e32 v10, v55
	v_pk_mul_f32 v[6:7], v[6:7], v[2:3] op_sel_hi:[1,0]
	v_pk_mul_f32 v[8:9], v[10:11], v[2:3] op_sel_hi:[1,0]
	v_pk_mul_f32 v[6:7], v[28:29], v[6:7]
	v_pk_mul_f32 v[8:9], v[30:31], v[8:9]
	v_cvt_pk_bf16_f32 v6, v6, v7
	v_cvt_pk_bf16_f32 v7, v8, v9
	global_store_dwordx4 v[12:13], v[4:7], off offset:128 nt
	s_branch .LBB0_497
